# GEMM K-loops: the two activation-tile LDS-DMA pieces of each 6-piece load segment issued first (before the fragment reads and the weight pieces)
# speedup vs baseline: 1.0047x; 1.0025x over previous
.Lskw_P1:
	s_waitcnt lgkmcnt(0)
	s_barrier
	s_setprio 1
	s_waitcnt lgkmcnt(0)
	v_mfma_f32_16x16x32_bf16 v[124:127], v[148:151], v[186:189], v[124:127]
	v_mfma_f32_16x16x32_bf16 v[120:123], v[156:159], v[186:189], v[120:123]
	v_mfma_f32_16x16x32_bf16 v[108:111], v[148:151], v[194:197], v[108:111]
	v_mfma_f32_16x16x32_bf16 v[104:107], v[156:159], v[194:197], v[104:107]
	v_mfma_f32_16x16x32_bf16 v[92:95], v[148:151], v[202:205], v[92:95]
	v_mfma_f32_16x16x32_bf16 v[88:91], v[156:159], v[202:205], v[88:91]
	v_mfma_f32_16x16x32_bf16 v[76:79], v[148:151], v[210:213], v[76:79]
	v_mfma_f32_16x16x32_bf16 v[72:75], v[156:159], v[210:213], v[72:75]
	v_mfma_f32_16x16x32_bf16 v[124:127], v[152:155], v[190:193], v[124:127]
	v_mfma_f32_16x16x32_bf16 v[120:123], v[160:163], v[190:193], v[120:123]
	v_mfma_f32_16x16x32_bf16 v[108:111], v[152:155], v[198:201], v[108:111]
	v_mfma_f32_16x16x32_bf16 v[104:107], v[160:163], v[198:201], v[104:107]
	v_mfma_f32_16x16x32_bf16 v[92:95], v[152:155], v[206:209], v[92:95]
	v_mfma_f32_16x16x32_bf16 v[88:91], v[160:163], v[206:209], v[88:91]
	v_mfma_f32_16x16x32_bf16 v[76:79], v[152:155], v[214:217], v[76:79]
	v_mfma_f32_16x16x32_bf16 v[72:75], v[160:163], v[214:217], v[72:75]
	s_setprio 0
	s_setprio 1
	v_mfma_f32_16x16x32_bf16 v[116:119], v[164:167], v[186:189], v[116:119]
	v_mfma_f32_16x16x32_bf16 v[112:115], v[178:181], v[186:189], v[112:115]
	v_mfma_f32_16x16x32_bf16 v[100:103], v[164:167], v[194:197], v[100:103]
	v_mfma_f32_16x16x32_bf16 v[96:99], v[178:181], v[194:197], v[96:99]
	v_mfma_f32_16x16x32_bf16 v[84:87], v[164:167], v[202:205], v[84:87]
	v_mfma_f32_16x16x32_bf16 v[80:83], v[178:181], v[202:205], v[80:83]
	v_mfma_f32_16x16x32_bf16 v[68:71], v[164:167], v[210:213], v[68:71]
	v_mfma_f32_16x16x32_bf16 v[64:67], v[178:181], v[210:213], v[64:67]
	v_mfma_f32_16x16x32_bf16 v[116:119], v[168:171], v[190:193], v[116:119]
	v_mfma_f32_16x16x32_bf16 v[112:115], v[182:185], v[190:193], v[112:115]
	v_mfma_f32_16x16x32_bf16 v[100:103], v[168:171], v[198:201], v[100:103]
	v_mfma_f32_16x16x32_bf16 v[96:99], v[182:185], v[198:201], v[96:99]
	v_mfma_f32_16x16x32_bf16 v[84:87], v[168:171], v[206:209], v[84:87]
	v_mfma_f32_16x16x32_bf16 v[80:83], v[182:185], v[206:209], v[80:83]
	v_mfma_f32_16x16x32_bf16 v[68:71], v[168:171], v[214:217], v[68:71]
	v_mfma_f32_16x16x32_bf16 v[64:67], v[182:185], v[214:217], v[64:67]
	s_setprio 0
	s_barrier
	v_lshl_add_u64 v[252:253], s[46:47], 0, v[128:129]
	s_mov_b32 m0, s51
	s_nop 0
	global_load_lds_dwordx4 v[252:253], off
	v_lshl_add_u64 v[252:253], s[46:47], 0, v[132:133]
	s_mov_b32 m0, s52
	s_nop 0
	global_load_lds_dwordx4 v[252:253], off
	s_add_i32 s27, s64, s50
	v_lshl_add_u64 v[218:219], s[44:45], 0, v[130:131]
	s_mov_b32 m0, s27
	ds_read_b128 v[186:189], v177 offset:16384
	ds_read_b128 v[190:193], v177 offset:17408
	ds_read_b128 v[194:197], v177 offset:18432
	ds_read_b128 v[198:201], v177 offset:19456
	ds_read_b128 v[202:205], v177 offset:20480
	ds_read_b128 v[206:209], v177 offset:21504
	ds_read_b128 v[210:213], v177 offset:22528
	ds_read_b128 v[214:217], v177 offset:23552
	global_load_lds_dwordx4 v[218:219], off
	s_add_i32 m0, s27, 0x2000
	s_add_u32 s34, s44, 0x40000
	v_lshl_add_u64 v[220:221], s[44:45], 0, v[134:135]
	s_addc_u32 s35, s45, 0
	s_add_i32 s27, s65, s50
	global_load_lds_dwordx4 v[220:221], off
	v_lshl_add_u64 v[222:223], s[34:35], 0, v[130:131]
	s_mov_b32 m0, s27
	v_lshl_add_u64 v[224:225], s[46:47], 0, v[132:133]
	global_load_lds_dwordx4 v[222:223], off
	v_lshl_add_u64 v[222:223], s[34:35], 0, v[134:135]
	s_add_i32 m0, s27, 0x2000
	s_nop 0
	global_load_lds_dwordx4 v[222:223], off
	v_lshl_add_u64 v[222:223], s[46:47], 0, v[128:129]
	s_waitcnt vmcnt(8)
	s_waitcnt lgkmcnt(0)
	s_barrier
	s_setprio 1
	s_waitcnt lgkmcnt(0)
	v_mfma_f32_16x16x32_bf16 v[60:63], v[148:151], v[186:189], v[60:63]
	v_mfma_f32_16x16x32_bf16 v[56:59], v[156:159], v[186:189], v[56:59]
	v_mfma_f32_16x16x32_bf16 v[44:47], v[148:151], v[194:197], v[44:47]
	v_mfma_f32_16x16x32_bf16 v[40:43], v[156:159], v[194:197], v[40:43]
	v_mfma_f32_16x16x32_bf16 v[28:31], v[148:151], v[202:205], v[28:31]
	v_mfma_f32_16x16x32_bf16 v[24:27], v[156:159], v[202:205], v[24:27]
	v_mfma_f32_16x16x32_bf16 v[12:15], v[148:151], v[210:213], v[12:15]
	v_mfma_f32_16x16x32_bf16 v[8:11], v[156:159], v[210:213], v[8:11]
	v_mfma_f32_16x16x32_bf16 v[60:63], v[152:155], v[190:193], v[60:63]
	v_mfma_f32_16x16x32_bf16 v[56:59], v[160:163], v[190:193], v[56:59]
	v_mfma_f32_16x16x32_bf16 v[44:47], v[152:155], v[198:201], v[44:47]
	v_mfma_f32_16x16x32_bf16 v[40:43], v[160:163], v[198:201], v[40:43]
	v_mfma_f32_16x16x32_bf16 v[28:31], v[152:155], v[206:209], v[28:31]
	v_mfma_f32_16x16x32_bf16 v[24:27], v[160:163], v[206:209], v[24:27]
	v_mfma_f32_16x16x32_bf16 v[12:15], v[152:155], v[214:217], v[12:15]
	v_mfma_f32_16x16x32_bf16 v[8:11], v[160:163], v[214:217], v[8:11]
	s_setprio 0
	s_setprio 1
	v_mfma_f32_16x16x32_bf16 v[52:55], v[164:167], v[186:189], v[52:55]
	v_mfma_f32_16x16x32_bf16 v[48:51], v[178:181], v[186:189], v[48:51]
	v_mfma_f32_16x16x32_bf16 v[36:39], v[164:167], v[194:197], v[36:39]
	v_mfma_f32_16x16x32_bf16 v[32:35], v[178:181], v[194:197], v[32:35]
	v_mfma_f32_16x16x32_bf16 v[20:23], v[164:167], v[202:205], v[20:23]
	v_mfma_f32_16x16x32_bf16 v[16:19], v[178:181], v[202:205], v[16:19]
	v_mfma_f32_16x16x32_bf16 v[4:7], v[164:167], v[210:213], v[4:7]
	v_mfma_f32_16x16x32_bf16 v[0:3], v[178:181], v[210:213], v[0:3]
	v_mfma_f32_16x16x32_bf16 v[52:55], v[168:171], v[190:193], v[52:55]
	v_mfma_f32_16x16x32_bf16 v[48:51], v[182:185], v[190:193], v[48:51]
	v_mfma_f32_16x16x32_bf16 v[36:39], v[168:171], v[198:201], v[36:39]
	v_mfma_f32_16x16x32_bf16 v[32:35], v[182:185], v[198:201], v[32:35]
	v_mfma_f32_16x16x32_bf16 v[20:23], v[168:171], v[206:209], v[20:23]
	v_mfma_f32_16x16x32_bf16 v[16:19], v[182:185], v[206:209], v[16:19]
	v_mfma_f32_16x16x32_bf16 v[4:7], v[168:171], v[214:217], v[4:7]
	v_mfma_f32_16x16x32_bf16 v[0:3], v[182:185], v[214:217], v[0:3]
	s_setprio 0
	s_barrier
	s_add_i32 s27, 0, 0x18000
	v_add_u32_e32 v136, s27, v173
	s_add_i32 s30, 0, 0x1c000
	ds_read_b128 v[148:151], v136
	ds_read_b128 v[152:155], v136 offset:1024
	ds_read_b128 v[156:159], v136 offset:2048
	ds_read_b128 v[160:163], v136 offset:3072
	v_add_u32_e32 v136, s30, v173
	ds_read_b128 v[164:167], v136
	ds_read_b128 v[168:171], v136 offset:1024
	ds_read_b128 v[178:181], v136 offset:2048
	ds_read_b128 v[182:185], v136 offset:3072
	s_add_u32 s34, s46, 0x40000
	s_addc_u32 s35, s47, 0
	s_mov_b32 m0, s53
	v_lshl_add_u64 v[226:227], s[34:35], 0, v[128:129]
	ds_read_b128 v[186:189], v177 offset:32768
	ds_read_b128 v[190:193], v177 offset:33792
	ds_read_b128 v[194:197], v177 offset:34816
	ds_read_b128 v[198:201], v177 offset:35840
	ds_read_b128 v[202:205], v177 offset:36864
	ds_read_b128 v[206:209], v177 offset:37888
	ds_read_b128 v[210:213], v177 offset:38912
	ds_read_b128 v[214:217], v177 offset:39936
	global_load_lds_dwordx4 v[226:227], off
	v_lshl_add_u64 v[226:227], s[34:35], 0, v[132:133]
	s_mov_b32 m0, s54
	s_nop 0
	global_load_lds_dwordx4 v[226:227], off
	s_waitcnt vmcnt(8)
	s_waitcnt lgkmcnt(0)
	s_barrier
	s_setprio 1
	s_waitcnt lgkmcnt(0)
	v_mfma_f32_16x16x32_bf16 v[124:127], v[148:151], v[186:189], v[124:127]
	v_mfma_f32_16x16x32_bf16 v[120:123], v[156:159], v[186:189], v[120:123]
	v_mfma_f32_16x16x32_bf16 v[108:111], v[148:151], v[194:197], v[108:111]
	v_mfma_f32_16x16x32_bf16 v[104:107], v[156:159], v[194:197], v[104:107]
	v_mfma_f32_16x16x32_bf16 v[92:95], v[148:151], v[202:205], v[92:95]
	v_mfma_f32_16x16x32_bf16 v[88:91], v[156:159], v[202:205], v[88:91]
	v_mfma_f32_16x16x32_bf16 v[76:79], v[148:151], v[210:213], v[76:79]
	v_mfma_f32_16x16x32_bf16 v[72:75], v[156:159], v[210:213], v[72:75]
	v_mfma_f32_16x16x32_bf16 v[124:127], v[152:155], v[190:193], v[124:127]
	v_mfma_f32_16x16x32_bf16 v[120:123], v[160:163], v[190:193], v[120:123]
	v_mfma_f32_16x16x32_bf16 v[108:111], v[152:155], v[198:201], v[108:111]
	v_mfma_f32_16x16x32_bf16 v[104:107], v[160:163], v[198:201], v[104:107]
	v_mfma_f32_16x16x32_bf16 v[92:95], v[152:155], v[206:209], v[92:95]
	v_mfma_f32_16x16x32_bf16 v[88:91], v[160:163], v[206:209], v[88:91]
	v_mfma_f32_16x16x32_bf16 v[76:79], v[152:155], v[214:217], v[76:79]
	v_mfma_f32_16x16x32_bf16 v[72:75], v[160:163], v[214:217], v[72:75]
	s_setprio 0
	s_setprio 1
	v_mfma_f32_16x16x32_bf16 v[116:119], v[164:167], v[186:189], v[116:119]
	v_mfma_f32_16x16x32_bf16 v[112:115], v[178:181], v[186:189], v[112:115]
	v_mfma_f32_16x16x32_bf16 v[100:103], v[164:167], v[194:197], v[100:103]
	v_mfma_f32_16x16x32_bf16 v[96:99], v[178:181], v[194:197], v[96:99]
	v_mfma_f32_16x16x32_bf16 v[84:87], v[164:167], v[202:205], v[84:87]
	v_mfma_f32_16x16x32_bf16 v[80:83], v[178:181], v[202:205], v[80:83]
	v_mfma_f32_16x16x32_bf16 v[68:71], v[164:167], v[210:213], v[68:71]
	v_mfma_f32_16x16x32_bf16 v[64:67], v[178:181], v[210:213], v[64:67]
	v_mfma_f32_16x16x32_bf16 v[116:119], v[168:171], v[190:193], v[116:119]
	v_mfma_f32_16x16x32_bf16 v[112:115], v[182:185], v[190:193], v[112:115]
	v_mfma_f32_16x16x32_bf16 v[100:103], v[168:171], v[198:201], v[100:103]
	v_mfma_f32_16x16x32_bf16 v[96:99], v[182:185], v[198:201], v[96:99]
	v_mfma_f32_16x16x32_bf16 v[84:87], v[168:171], v[206:209], v[84:87]
	v_mfma_f32_16x16x32_bf16 v[80:83], v[182:185], v[206:209], v[80:83]
	v_mfma_f32_16x16x32_bf16 v[68:71], v[168:171], v[214:217], v[68:71]
	v_mfma_f32_16x16x32_bf16 v[64:67], v[182:185], v[214:217], v[64:67]
	s_setprio 0
	s_barrier
	v_lshl_add_u64 v[252:253], v[222:223], 0, s[20:21]
	s_mov_b32 m0, s62
	s_nop 0
	global_load_lds_dwordx4 v[252:253], off
	v_lshl_add_u64 v[252:253], v[224:225], 0, s[20:21]
	s_mov_b32 m0, s63
	s_nop 0
	global_load_lds_dwordx4 v[252:253], off
	s_add_i32 s27, s27, s50
	v_lshl_add_u64 v[218:219], v[218:219], 0, s[20:21]
	s_mov_b32 m0, s27
	ds_read_b128 v[186:189], v177 offset:49152
	ds_read_b128 v[190:193], v177 offset:50176
	ds_read_b128 v[194:197], v177 offset:51200
	ds_read_b128 v[198:201], v177 offset:52224
	ds_read_b128 v[202:205], v177 offset:53248
	ds_read_b128 v[206:209], v177 offset:54272
	ds_read_b128 v[210:213], v177 offset:55296
	ds_read_b128 v[214:217], v177 offset:56320
	global_load_lds_dwordx4 v[218:219], off
	s_add_i32 m0, s27, 0x2000
	s_add_u32 s34, s44, 0x40080
	v_lshl_add_u64 v[218:219], v[220:221], 0, s[20:21]
	s_addc_u32 s35, s45, 0
	s_add_i32 s27, s30, s50
	global_load_lds_dwordx4 v[218:219], off
	v_lshl_add_u64 v[218:219], s[34:35], 0, v[130:131]
	s_mov_b32 m0, s27
	s_nop 0
	global_load_lds_dwordx4 v[218:219], off
	v_lshl_add_u64 v[218:219], s[34:35], 0, v[134:135]
	s_add_i32 m0, s27, 0x2000
	s_nop 0
	global_load_lds_dwordx4 v[218:219], off
	v_lshl_add_u64 v[218:219], v[222:223], 0, s[20:21]
	v_lshl_add_u64 v[218:219], v[224:225], 0, s[20:21]
	s_waitcnt vmcnt(8)
	s_waitcnt lgkmcnt(0)
	s_barrier
	s_setprio 1
	s_waitcnt lgkmcnt(0)
	v_mfma_f32_16x16x32_bf16 v[60:63], v[148:151], v[186:189], v[60:63]
	v_mfma_f32_16x16x32_bf16 v[56:59], v[156:159], v[186:189], v[56:59]
	v_mfma_f32_16x16x32_bf16 v[44:47], v[148:151], v[194:197], v[44:47]
	v_mfma_f32_16x16x32_bf16 v[40:43], v[156:159], v[194:197], v[40:43]
	v_mfma_f32_16x16x32_bf16 v[28:31], v[148:151], v[202:205], v[28:31]
	v_mfma_f32_16x16x32_bf16 v[24:27], v[156:159], v[202:205], v[24:27]
	v_mfma_f32_16x16x32_bf16 v[12:15], v[148:151], v[210:213], v[12:15]
	v_mfma_f32_16x16x32_bf16 v[8:11], v[156:159], v[210:213], v[8:11]
	v_mfma_f32_16x16x32_bf16 v[60:63], v[152:155], v[190:193], v[60:63]
	v_mfma_f32_16x16x32_bf16 v[56:59], v[160:163], v[190:193], v[56:59]
	v_mfma_f32_16x16x32_bf16 v[44:47], v[152:155], v[198:201], v[44:47]
	v_mfma_f32_16x16x32_bf16 v[40:43], v[160:163], v[198:201], v[40:43]
	v_mfma_f32_16x16x32_bf16 v[28:31], v[152:155], v[206:209], v[28:31]
	v_mfma_f32_16x16x32_bf16 v[24:27], v[160:163], v[206:209], v[24:27]
	v_mfma_f32_16x16x32_bf16 v[12:15], v[152:155], v[214:217], v[12:15]
	v_mfma_f32_16x16x32_bf16 v[8:11], v[160:163], v[214:217], v[8:11]
	s_setprio 0
	s_setprio 1
	v_mfma_f32_16x16x32_bf16 v[52:55], v[164:167], v[186:189], v[52:55]
	v_mfma_f32_16x16x32_bf16 v[48:51], v[178:181], v[186:189], v[48:51]
	v_mfma_f32_16x16x32_bf16 v[36:39], v[164:167], v[194:197], v[36:39]
	v_mfma_f32_16x16x32_bf16 v[32:35], v[178:181], v[194:197], v[32:35]
	v_mfma_f32_16x16x32_bf16 v[20:23], v[164:167], v[202:205], v[20:23]
	v_mfma_f32_16x16x32_bf16 v[16:19], v[178:181], v[202:205], v[16:19]
	v_mfma_f32_16x16x32_bf16 v[4:7], v[164:167], v[210:213], v[4:7]
	v_mfma_f32_16x16x32_bf16 v[0:3], v[178:181], v[210:213], v[0:3]
	v_mfma_f32_16x16x32_bf16 v[52:55], v[168:171], v[190:193], v[52:55]
	v_mfma_f32_16x16x32_bf16 v[48:51], v[182:185], v[190:193], v[48:51]
	v_mfma_f32_16x16x32_bf16 v[36:39], v[168:171], v[198:201], v[36:39]
	v_mfma_f32_16x16x32_bf16 v[32:35], v[182:185], v[198:201], v[32:35]
	v_mfma_f32_16x16x32_bf16 v[20:23], v[168:171], v[206:209], v[20:23]
	v_mfma_f32_16x16x32_bf16 v[16:19], v[182:185], v[206:209], v[16:19]
	v_mfma_f32_16x16x32_bf16 v[4:7], v[168:171], v[214:217], v[4:7]
	v_mfma_f32_16x16x32_bf16 v[0:3], v[182:185], v[214:217], v[0:3]
	s_setprio 0
	s_barrier
	s_add_i32 s25, s25, 2
	s_add_u32 s42, s42, 0x100
	s_addc_u32 s43, s43, 0
	s_add_u32 s23, s23, 0x100
	s_addc_u32 s24, s24, 0
	s_cmp_gt_u32 s25, 13
	s_cbranch_scc0 .LBB5_248
	s_nop 0
	s_nop 0
	s_nop 0
	s_nop 0
	s_nop 0
	s_nop 0
	s_nop 0
	s_nop 0
	s_nop 0
	s_nop 0
	s_nop 0
	s_nop 0
	s_nop 0
	s_nop 0
	s_nop 0
	s_nop 0
	s_nop 0
	s_nop 0
	s_nop 0
	s_nop 0
	s_nop 0
	s_nop 0
	s_and_b64 vcc, exec, s[18:19]
	s_cbranch_vccz .LBB5_251
	s_barrier

.Lskw_P3:
	s_waitcnt lgkmcnt(0)
	s_barrier
	s_setprio 1
	s_waitcnt lgkmcnt(0)
	v_mfma_f32_16x16x32_bf16 v[156:159], v[64:67], v[160:163], v[156:159]
	v_mfma_f32_16x16x32_bf16 v[152:155], v[72:75], v[160:163], v[152:155]
	v_mfma_f32_16x16x32_bf16 v[124:127], v[64:67], v[168:171], v[124:127]
	v_mfma_f32_16x16x32_bf16 v[120:123], v[72:75], v[168:171], v[120:123]
	v_mfma_f32_16x16x32_bf16 v[108:111], v[64:67], v[176:179], v[108:111]
	v_mfma_f32_16x16x32_bf16 v[104:107], v[72:75], v[176:179], v[104:107]
	v_mfma_f32_16x16x32_bf16 v[92:95], v[64:67], v[184:187], v[92:95]
	v_mfma_f32_16x16x32_bf16 v[88:91], v[72:75], v[184:187], v[88:91]
	v_mfma_f32_16x16x32_bf16 v[156:159], v[68:71], v[164:167], v[156:159]
	v_mfma_f32_16x16x32_bf16 v[152:155], v[76:79], v[164:167], v[152:155]
	v_mfma_f32_16x16x32_bf16 v[124:127], v[68:71], v[172:175], v[124:127]
	v_mfma_f32_16x16x32_bf16 v[120:123], v[76:79], v[172:175], v[120:123]
	v_mfma_f32_16x16x32_bf16 v[108:111], v[68:71], v[180:183], v[108:111]
	v_mfma_f32_16x16x32_bf16 v[104:107], v[76:79], v[180:183], v[104:107]
	v_mfma_f32_16x16x32_bf16 v[92:95], v[68:71], v[188:191], v[92:95]
	v_mfma_f32_16x16x32_bf16 v[88:91], v[76:79], v[188:191], v[88:91]
	s_setprio 0
	s_setprio 1
	v_mfma_f32_16x16x32_bf16 v[132:135], v[136:139], v[160:163], v[132:135]
	v_mfma_f32_16x16x32_bf16 v[128:131], v[144:147], v[160:163], v[128:131]
	v_mfma_f32_16x16x32_bf16 v[116:119], v[136:139], v[168:171], v[116:119]
	v_mfma_f32_16x16x32_bf16 v[112:115], v[144:147], v[168:171], v[112:115]
	v_mfma_f32_16x16x32_bf16 v[100:103], v[136:139], v[176:179], v[100:103]
	v_mfma_f32_16x16x32_bf16 v[96:99], v[144:147], v[176:179], v[96:99]
	v_mfma_f32_16x16x32_bf16 v[84:87], v[136:139], v[184:187], v[84:87]
	v_mfma_f32_16x16x32_bf16 v[80:83], v[144:147], v[184:187], v[80:83]
	v_mfma_f32_16x16x32_bf16 v[132:135], v[140:143], v[164:167], v[132:135]
	v_mfma_f32_16x16x32_bf16 v[128:131], v[148:151], v[164:167], v[128:131]
	v_mfma_f32_16x16x32_bf16 v[116:119], v[140:143], v[172:175], v[116:119]
	v_mfma_f32_16x16x32_bf16 v[112:115], v[148:151], v[172:175], v[112:115]
	v_mfma_f32_16x16x32_bf16 v[100:103], v[140:143], v[180:183], v[100:103]
	v_mfma_f32_16x16x32_bf16 v[96:99], v[148:151], v[180:183], v[96:99]
	v_mfma_f32_16x16x32_bf16 v[84:87], v[140:143], v[188:191], v[84:87]
	v_mfma_f32_16x16x32_bf16 v[80:83], v[148:151], v[188:191], v[80:83]
	s_setprio 0
	s_barrier
	v_lshl_add_u64 v[252:253], s[44:45], 0, v[200:201]
	s_mov_b32 m0, s39
	s_nop 0
	global_load_lds_dwordx4 v[252:253], off
	v_lshl_add_u64 v[252:253], s[44:45], 0, v[204:205]
	s_mov_b32 m0, s48
	s_nop 0
	global_load_lds_dwordx4 v[252:253], off
	s_add_i32 s35, s55, s46
	v_lshl_add_u64 v[192:193], s[42:43], 0, v[202:203]
	s_mov_b32 m0, s35
	ds_read_b128 v[160:163], v231 offset:16384
	ds_read_b128 v[164:167], v231 offset:17408
	ds_read_b128 v[168:171], v231 offset:18432
	ds_read_b128 v[172:175], v231 offset:19456
	ds_read_b128 v[176:179], v231 offset:20480
	ds_read_b128 v[180:183], v231 offset:21504
	ds_read_b128 v[184:187], v231 offset:22528
	ds_read_b128 v[188:191], v231 offset:23552
	global_load_lds_dwordx4 v[192:193], off
	s_add_i32 m0, s35, 0x2000
	s_add_u32 s58, s42, 0x40000
	v_lshl_add_u64 v[194:195], s[42:43], 0, v[206:207]
	s_addc_u32 s59, s43, 0
	s_add_i32 s35, s56, s46
	global_load_lds_dwordx4 v[194:195], off
	v_lshl_add_u64 v[196:197], s[58:59], 0, v[202:203]
	s_mov_b32 m0, s35
	v_lshl_add_u64 v[198:199], s[44:45], 0, v[204:205]
	global_load_lds_dwordx4 v[196:197], off
	v_lshl_add_u64 v[196:197], s[58:59], 0, v[206:207]
	s_add_i32 m0, s35, 0x2000
	s_nop 0
	global_load_lds_dwordx4 v[196:197], off
	v_lshl_add_u64 v[196:197], s[44:45], 0, v[200:201]
	s_waitcnt vmcnt(8)
	s_waitcnt lgkmcnt(0)
	s_barrier
	s_setprio 1
	s_waitcnt lgkmcnt(0)
	v_mfma_f32_16x16x32_bf16 v[60:63], v[64:67], v[160:163], v[60:63]
	v_mfma_f32_16x16x32_bf16 v[56:59], v[72:75], v[160:163], v[56:59]
	v_mfma_f32_16x16x32_bf16 v[44:47], v[64:67], v[168:171], v[44:47]
	v_mfma_f32_16x16x32_bf16 v[40:43], v[72:75], v[168:171], v[40:43]
	v_mfma_f32_16x16x32_bf16 v[28:31], v[64:67], v[176:179], v[28:31]
	v_mfma_f32_16x16x32_bf16 v[24:27], v[72:75], v[176:179], v[24:27]
	v_mfma_f32_16x16x32_bf16 v[12:15], v[64:67], v[184:187], v[12:15]
	v_mfma_f32_16x16x32_bf16 v[8:11], v[72:75], v[184:187], v[8:11]
	v_mfma_f32_16x16x32_bf16 v[60:63], v[68:71], v[164:167], v[60:63]
	v_mfma_f32_16x16x32_bf16 v[56:59], v[76:79], v[164:167], v[56:59]
	v_mfma_f32_16x16x32_bf16 v[44:47], v[68:71], v[172:175], v[44:47]
	v_mfma_f32_16x16x32_bf16 v[40:43], v[76:79], v[172:175], v[40:43]
	v_mfma_f32_16x16x32_bf16 v[28:31], v[68:71], v[180:183], v[28:31]
	v_mfma_f32_16x16x32_bf16 v[24:27], v[76:79], v[180:183], v[24:27]
	v_mfma_f32_16x16x32_bf16 v[12:15], v[68:71], v[188:191], v[12:15]
	v_mfma_f32_16x16x32_bf16 v[8:11], v[76:79], v[188:191], v[8:11]
	s_setprio 0
	s_setprio 1
	v_mfma_f32_16x16x32_bf16 v[52:55], v[136:139], v[160:163], v[52:55]
	v_mfma_f32_16x16x32_bf16 v[48:51], v[144:147], v[160:163], v[48:51]
	v_mfma_f32_16x16x32_bf16 v[36:39], v[136:139], v[168:171], v[36:39]
	v_mfma_f32_16x16x32_bf16 v[32:35], v[144:147], v[168:171], v[32:35]
	v_mfma_f32_16x16x32_bf16 v[20:23], v[136:139], v[176:179], v[20:23]
	v_mfma_f32_16x16x32_bf16 v[16:19], v[144:147], v[176:179], v[16:19]
	v_mfma_f32_16x16x32_bf16 v[4:7], v[136:139], v[184:187], v[4:7]
	v_mfma_f32_16x16x32_bf16 v[0:3], v[144:147], v[184:187], v[0:3]
	v_mfma_f32_16x16x32_bf16 v[52:55], v[140:143], v[164:167], v[52:55]
	v_mfma_f32_16x16x32_bf16 v[48:51], v[148:151], v[164:167], v[48:51]
	v_mfma_f32_16x16x32_bf16 v[36:39], v[140:143], v[172:175], v[36:39]
	v_mfma_f32_16x16x32_bf16 v[32:35], v[148:151], v[172:175], v[32:35]
	v_mfma_f32_16x16x32_bf16 v[20:23], v[140:143], v[180:183], v[20:23]
	v_mfma_f32_16x16x32_bf16 v[16:19], v[148:151], v[180:183], v[16:19]
	v_mfma_f32_16x16x32_bf16 v[4:7], v[140:143], v[188:191], v[4:7]
	v_mfma_f32_16x16x32_bf16 v[0:3], v[148:151], v[188:191], v[0:3]
	s_setprio 0
	s_barrier
	s_add_i32 s35, 0, 0x18000
	s_add_i32 s57, 0, 0x1c000
	v_add_u32_e32 v76, s35, v227
	v_add_u32_e32 v148, s57, v227
	ds_read_b128 v[64:67], v76
	ds_read_b128 v[68:71], v76 offset:1024
	ds_read_b128 v[72:75], v76 offset:2048
	ds_read_b128 v[76:79], v76 offset:3072
	ds_read_b128 v[136:139], v148
	ds_read_b128 v[140:143], v148 offset:1024
	ds_read_b128 v[144:147], v148 offset:2048
	ds_read_b128 v[148:151], v148 offset:3072
	s_add_u32 s44, s44, 0x40000
	s_addc_u32 s45, s45, 0
	s_mov_b32 m0, s49
	v_lshl_add_u64 v[216:217], s[44:45], 0, v[200:201]
	ds_read_b128 v[160:163], v231 offset:32768
	ds_read_b128 v[164:167], v231 offset:33792
	ds_read_b128 v[168:171], v231 offset:34816
	ds_read_b128 v[172:175], v231 offset:35840
	ds_read_b128 v[176:179], v231 offset:36864
	ds_read_b128 v[180:183], v231 offset:37888
	ds_read_b128 v[184:187], v231 offset:38912
	ds_read_b128 v[188:191], v231 offset:39936
	global_load_lds_dwordx4 v[216:217], off
	v_lshl_add_u64 v[216:217], s[44:45], 0, v[204:205]
	s_mov_b32 m0, s50
	s_nop 0
	global_load_lds_dwordx4 v[216:217], off
	s_waitcnt vmcnt(8)
	s_waitcnt lgkmcnt(0)
	s_barrier
	s_setprio 1
	s_waitcnt lgkmcnt(0)
	v_mfma_f32_16x16x32_bf16 v[156:159], v[64:67], v[160:163], v[156:159]
	v_mfma_f32_16x16x32_bf16 v[152:155], v[72:75], v[160:163], v[152:155]
	v_mfma_f32_16x16x32_bf16 v[124:127], v[64:67], v[168:171], v[124:127]
	v_mfma_f32_16x16x32_bf16 v[120:123], v[72:75], v[168:171], v[120:123]
	v_mfma_f32_16x16x32_bf16 v[108:111], v[64:67], v[176:179], v[108:111]
	v_mfma_f32_16x16x32_bf16 v[104:107], v[72:75], v[176:179], v[104:107]
	v_mfma_f32_16x16x32_bf16 v[92:95], v[64:67], v[184:187], v[92:95]
	v_mfma_f32_16x16x32_bf16 v[88:91], v[72:75], v[184:187], v[88:91]
	v_mfma_f32_16x16x32_bf16 v[156:159], v[68:71], v[164:167], v[156:159]
	v_mfma_f32_16x16x32_bf16 v[152:155], v[76:79], v[164:167], v[152:155]
	v_mfma_f32_16x16x32_bf16 v[124:127], v[68:71], v[172:175], v[124:127]
	v_mfma_f32_16x16x32_bf16 v[120:123], v[76:79], v[172:175], v[120:123]
	v_mfma_f32_16x16x32_bf16 v[108:111], v[68:71], v[180:183], v[108:111]
	v_mfma_f32_16x16x32_bf16 v[104:107], v[76:79], v[180:183], v[104:107]
	v_mfma_f32_16x16x32_bf16 v[92:95], v[68:71], v[188:191], v[92:95]
	v_mfma_f32_16x16x32_bf16 v[88:91], v[76:79], v[188:191], v[88:91]
	s_setprio 0
	s_setprio 1
	v_mfma_f32_16x16x32_bf16 v[132:135], v[136:139], v[160:163], v[132:135]
	v_mfma_f32_16x16x32_bf16 v[128:131], v[144:147], v[160:163], v[128:131]
	v_mfma_f32_16x16x32_bf16 v[116:119], v[136:139], v[168:171], v[116:119]
	v_mfma_f32_16x16x32_bf16 v[112:115], v[144:147], v[168:171], v[112:115]
	v_mfma_f32_16x16x32_bf16 v[100:103], v[136:139], v[176:179], v[100:103]
	v_mfma_f32_16x16x32_bf16 v[96:99], v[144:147], v[176:179], v[96:99]
	v_mfma_f32_16x16x32_bf16 v[84:87], v[136:139], v[184:187], v[84:87]
	v_mfma_f32_16x16x32_bf16 v[80:83], v[144:147], v[184:187], v[80:83]
	v_mfma_f32_16x16x32_bf16 v[132:135], v[140:143], v[164:167], v[132:135]
	v_mfma_f32_16x16x32_bf16 v[128:131], v[148:151], v[164:167], v[128:131]
	v_mfma_f32_16x16x32_bf16 v[116:119], v[140:143], v[172:175], v[116:119]
	v_mfma_f32_16x16x32_bf16 v[112:115], v[148:151], v[172:175], v[112:115]
	v_mfma_f32_16x16x32_bf16 v[100:103], v[140:143], v[180:183], v[100:103]
	v_mfma_f32_16x16x32_bf16 v[96:99], v[148:151], v[180:183], v[96:99]
	v_mfma_f32_16x16x32_bf16 v[84:87], v[140:143], v[188:191], v[84:87]
	v_mfma_f32_16x16x32_bf16 v[80:83], v[148:151], v[188:191], v[80:83]
	s_setprio 0
	s_barrier
	v_lshl_add_u64 v[252:253], v[196:197], 0, s[16:17]
	s_mov_b32 m0, s53
	s_nop 0
	global_load_lds_dwordx4 v[252:253], off
	v_lshl_add_u64 v[252:253], v[198:199], 0, s[16:17]
	s_mov_b32 m0, s54
	s_nop 0
	global_load_lds_dwordx4 v[252:253], off
	s_add_i32 s35, s35, s46
	v_lshl_add_u64 v[192:193], v[192:193], 0, s[16:17]
	s_mov_b32 m0, s35
	ds_read_b128 v[160:163], v231 offset:49152
	ds_read_b128 v[164:167], v231 offset:50176
	ds_read_b128 v[168:171], v231 offset:51200
	ds_read_b128 v[172:175], v231 offset:52224
	ds_read_b128 v[176:179], v231 offset:53248
	ds_read_b128 v[180:183], v231 offset:54272
	ds_read_b128 v[184:187], v231 offset:55296
	ds_read_b128 v[188:191], v231 offset:56320
	global_load_lds_dwordx4 v[192:193], off
	s_add_i32 m0, s35, 0x2000
	s_add_u32 s42, s42, 0x40080
	v_lshl_add_u64 v[192:193], v[194:195], 0, s[16:17]
	s_addc_u32 s43, s43, 0
	s_add_i32 s35, s57, s46
	global_load_lds_dwordx4 v[192:193], off
	v_lshl_add_u64 v[192:193], s[42:43], 0, v[202:203]
	s_mov_b32 m0, s35
	s_nop 0
	global_load_lds_dwordx4 v[192:193], off
	v_lshl_add_u64 v[192:193], s[42:43], 0, v[206:207]
	s_add_i32 m0, s35, 0x2000
	s_nop 0
	global_load_lds_dwordx4 v[192:193], off
	v_lshl_add_u64 v[192:193], v[196:197], 0, s[16:17]
	v_lshl_add_u64 v[192:193], v[198:199], 0, s[16:17]
	s_waitcnt vmcnt(8)
	s_waitcnt lgkmcnt(0)
	s_barrier
	s_setprio 1
	s_waitcnt lgkmcnt(0)
	v_mfma_f32_16x16x32_bf16 v[60:63], v[64:67], v[160:163], v[60:63]
	v_mfma_f32_16x16x32_bf16 v[56:59], v[72:75], v[160:163], v[56:59]
	v_mfma_f32_16x16x32_bf16 v[44:47], v[64:67], v[168:171], v[44:47]
	v_mfma_f32_16x16x32_bf16 v[40:43], v[72:75], v[168:171], v[40:43]
	v_mfma_f32_16x16x32_bf16 v[28:31], v[64:67], v[176:179], v[28:31]
	v_mfma_f32_16x16x32_bf16 v[24:27], v[72:75], v[176:179], v[24:27]
	v_mfma_f32_16x16x32_bf16 v[12:15], v[64:67], v[184:187], v[12:15]
	v_mfma_f32_16x16x32_bf16 v[8:11], v[72:75], v[184:187], v[8:11]
	v_mfma_f32_16x16x32_bf16 v[60:63], v[68:71], v[164:167], v[60:63]
	v_mfma_f32_16x16x32_bf16 v[56:59], v[76:79], v[164:167], v[56:59]
	v_mfma_f32_16x16x32_bf16 v[44:47], v[68:71], v[172:175], v[44:47]
	v_mfma_f32_16x16x32_bf16 v[40:43], v[76:79], v[172:175], v[40:43]
	v_mfma_f32_16x16x32_bf16 v[28:31], v[68:71], v[180:183], v[28:31]
	v_mfma_f32_16x16x32_bf16 v[24:27], v[76:79], v[180:183], v[24:27]
	v_mfma_f32_16x16x32_bf16 v[12:15], v[68:71], v[188:191], v[12:15]
	v_mfma_f32_16x16x32_bf16 v[8:11], v[76:79], v[188:191], v[8:11]
	s_setprio 0
	s_setprio 1
	v_mfma_f32_16x16x32_bf16 v[52:55], v[136:139], v[160:163], v[52:55]
	v_mfma_f32_16x16x32_bf16 v[48:51], v[144:147], v[160:163], v[48:51]
	v_mfma_f32_16x16x32_bf16 v[36:39], v[136:139], v[168:171], v[36:39]
	v_mfma_f32_16x16x32_bf16 v[32:35], v[144:147], v[168:171], v[32:35]
	v_mfma_f32_16x16x32_bf16 v[20:23], v[136:139], v[176:179], v[20:23]
	v_mfma_f32_16x16x32_bf16 v[16:19], v[144:147], v[176:179], v[16:19]
	v_mfma_f32_16x16x32_bf16 v[4:7], v[136:139], v[184:187], v[4:7]
	v_mfma_f32_16x16x32_bf16 v[0:3], v[144:147], v[184:187], v[0:3]
	v_mfma_f32_16x16x32_bf16 v[52:55], v[140:143], v[164:167], v[52:55]
	v_mfma_f32_16x16x32_bf16 v[48:51], v[148:151], v[164:167], v[48:51]
	v_mfma_f32_16x16x32_bf16 v[36:39], v[140:143], v[172:175], v[36:39]
	v_mfma_f32_16x16x32_bf16 v[32:35], v[148:151], v[172:175], v[32:35]
	v_mfma_f32_16x16x32_bf16 v[20:23], v[140:143], v[180:183], v[20:23]
	v_mfma_f32_16x16x32_bf16 v[16:19], v[148:151], v[180:183], v[16:19]
	v_mfma_f32_16x16x32_bf16 v[4:7], v[140:143], v[188:191], v[4:7]
	v_mfma_f32_16x16x32_bf16 v[0:3], v[148:151], v[188:191], v[0:3]
	s_setprio 0
	s_barrier
	s_add_i32 s34, s34, 2
	s_add_u32 s40, s40, 0x100
	s_addc_u32 s41, s41, 0
	s_add_u32 s30, s30, 0x100
	s_addc_u32 s33, s33, 0
	s_cmp_gt_u32 s34, 13
	s_cbranch_scc0 .LBB5_463
	s_nop 0
	s_nop 0
	s_nop 0
	s_nop 0
	s_nop 0
	s_nop 0
	s_nop 0
	s_nop 0
	s_nop 0
	s_nop 0
	s_nop 0
	s_nop 0
	s_nop 0
	s_nop 0
	s_nop 0
	s_nop 0
	s_nop 0
	s_nop 0
	s_nop 0
	s_nop 0
	s_nop 0
	s_nop 0
	s_and_b64 vcc, exec, s[14:15]
	s_cbranch_vccz .LBB5_466
	s_barrier

.Lskw_P4:
	s_waitcnt lgkmcnt(0)
	s_barrier
	s_setprio 1
	s_waitcnt lgkmcnt(0)
	v_mfma_f32_16x16x32_bf16 v[124:127], v[128:131], v[160:163], v[124:127]
	v_mfma_f32_16x16x32_bf16 v[120:123], v[136:139], v[160:163], v[120:123]
	v_mfma_f32_16x16x32_bf16 v[108:111], v[128:131], v[168:171], v[108:111]
	v_mfma_f32_16x16x32_bf16 v[104:107], v[136:139], v[168:171], v[104:107]
	v_mfma_f32_16x16x32_bf16 v[92:95], v[128:131], v[192:195], v[92:95]
	v_mfma_f32_16x16x32_bf16 v[88:91], v[136:139], v[192:195], v[88:91]
	v_mfma_f32_16x16x32_bf16 v[76:79], v[128:131], v[200:203], v[76:79]
	v_mfma_f32_16x16x32_bf16 v[72:75], v[136:139], v[200:203], v[72:75]
	v_mfma_f32_16x16x32_bf16 v[124:127], v[132:135], v[164:167], v[124:127]
	v_mfma_f32_16x16x32_bf16 v[120:123], v[140:143], v[164:167], v[120:123]
	v_mfma_f32_16x16x32_bf16 v[108:111], v[132:135], v[172:175], v[108:111]
	v_mfma_f32_16x16x32_bf16 v[104:107], v[140:143], v[172:175], v[104:107]
	v_mfma_f32_16x16x32_bf16 v[92:95], v[132:135], v[196:199], v[92:95]
	v_mfma_f32_16x16x32_bf16 v[88:91], v[140:143], v[196:199], v[88:91]
	v_mfma_f32_16x16x32_bf16 v[76:79], v[132:135], v[212:215], v[76:79]
	v_mfma_f32_16x16x32_bf16 v[72:75], v[140:143], v[212:215], v[72:75]
	s_setprio 0
	s_setprio 1
	v_mfma_f32_16x16x32_bf16 v[116:119], v[144:147], v[160:163], v[116:119]
	v_mfma_f32_16x16x32_bf16 v[112:115], v[152:155], v[160:163], v[112:115]
	v_mfma_f32_16x16x32_bf16 v[100:103], v[144:147], v[168:171], v[100:103]
	v_mfma_f32_16x16x32_bf16 v[96:99], v[152:155], v[168:171], v[96:99]
	v_mfma_f32_16x16x32_bf16 v[84:87], v[144:147], v[192:195], v[84:87]
	v_mfma_f32_16x16x32_bf16 v[80:83], v[152:155], v[192:195], v[80:83]
	v_mfma_f32_16x16x32_bf16 v[68:71], v[144:147], v[200:203], v[68:71]
	v_mfma_f32_16x16x32_bf16 v[64:67], v[152:155], v[200:203], v[64:67]
	v_mfma_f32_16x16x32_bf16 v[116:119], v[148:151], v[164:167], v[116:119]
	v_mfma_f32_16x16x32_bf16 v[112:115], v[156:159], v[164:167], v[112:115]
	v_mfma_f32_16x16x32_bf16 v[100:103], v[148:151], v[172:175], v[100:103]
	v_mfma_f32_16x16x32_bf16 v[96:99], v[156:159], v[172:175], v[96:99]
	v_mfma_f32_16x16x32_bf16 v[84:87], v[148:151], v[196:199], v[84:87]
	v_mfma_f32_16x16x32_bf16 v[80:83], v[156:159], v[196:199], v[80:83]
	v_mfma_f32_16x16x32_bf16 v[68:71], v[148:151], v[212:215], v[68:71]
	v_mfma_f32_16x16x32_bf16 v[64:67], v[156:159], v[212:215], v[64:67]
	s_setprio 0
	s_barrier
	v_lshl_add_u64 v[252:253], s[44:45], 0, v[176:177]
	s_mov_b32 m0, s31
	s_nop 0
	global_load_lds_dwordx4 v[252:253], off
	v_lshl_add_u64 v[252:253], s[44:45], 0, v[180:181]
	s_mov_b32 m0, s33
	s_nop 0
	global_load_lds_dwordx4 v[252:253], off
	s_add_i32 s58, s51, s30
	v_lshl_add_u64 v[216:217], s[42:43], 0, v[178:179]
	s_mov_b32 m0, s58
	ds_read_b128 v[160:163], v211 offset:16384
	ds_read_b128 v[164:167], v211 offset:17408
	ds_read_b128 v[168:171], v211 offset:18432
	ds_read_b128 v[172:175], v211 offset:19456
	ds_read_b128 v[192:195], v211 offset:20480
	ds_read_b128 v[196:199], v211 offset:21504
	ds_read_b128 v[200:203], v211 offset:22528
	ds_read_b128 v[212:215], v211 offset:23552
	global_load_lds_dwordx4 v[216:217], off
	s_add_i32 m0, s58, 0x2000
	s_add_u32 s58, s42, 0x40000
	v_lshl_add_u64 v[218:219], s[42:43], 0, v[182:183]
	s_addc_u32 s59, s43, 0
	s_add_i32 s60, s52, s30
	global_load_lds_dwordx4 v[218:219], off
	v_lshl_add_u64 v[220:221], s[58:59], 0, v[178:179]
	s_mov_b32 m0, s60
	v_lshl_add_u64 v[222:223], s[44:45], 0, v[180:181]
	global_load_lds_dwordx4 v[220:221], off
	v_lshl_add_u64 v[220:221], s[58:59], 0, v[182:183]
	s_add_i32 m0, s60, 0x2000
	s_nop 0
	global_load_lds_dwordx4 v[220:221], off
	v_lshl_add_u64 v[220:221], s[44:45], 0, v[176:177]
	s_waitcnt vmcnt(8)
	s_waitcnt lgkmcnt(0)
	s_barrier
	s_setprio 1
	s_waitcnt lgkmcnt(0)
	v_mfma_f32_16x16x32_bf16 v[60:63], v[128:131], v[160:163], v[60:63]
	v_mfma_f32_16x16x32_bf16 v[56:59], v[136:139], v[160:163], v[56:59]
	v_mfma_f32_16x16x32_bf16 v[44:47], v[128:131], v[168:171], v[44:47]
	v_mfma_f32_16x16x32_bf16 v[40:43], v[136:139], v[168:171], v[40:43]
	v_mfma_f32_16x16x32_bf16 v[28:31], v[128:131], v[192:195], v[28:31]
	v_mfma_f32_16x16x32_bf16 v[24:27], v[136:139], v[192:195], v[24:27]
	v_mfma_f32_16x16x32_bf16 v[12:15], v[128:131], v[200:203], v[12:15]
	v_mfma_f32_16x16x32_bf16 v[8:11], v[136:139], v[200:203], v[8:11]
	v_mfma_f32_16x16x32_bf16 v[60:63], v[132:135], v[164:167], v[60:63]
	v_mfma_f32_16x16x32_bf16 v[56:59], v[140:143], v[164:167], v[56:59]
	v_mfma_f32_16x16x32_bf16 v[44:47], v[132:135], v[172:175], v[44:47]
	v_mfma_f32_16x16x32_bf16 v[40:43], v[140:143], v[172:175], v[40:43]
	v_mfma_f32_16x16x32_bf16 v[28:31], v[132:135], v[196:199], v[28:31]
	v_mfma_f32_16x16x32_bf16 v[24:27], v[140:143], v[196:199], v[24:27]
	v_mfma_f32_16x16x32_bf16 v[12:15], v[132:135], v[212:215], v[12:15]
	v_mfma_f32_16x16x32_bf16 v[8:11], v[140:143], v[212:215], v[8:11]
	s_setprio 0
	s_setprio 1
	v_mfma_f32_16x16x32_bf16 v[52:55], v[144:147], v[160:163], v[52:55]
	v_mfma_f32_16x16x32_bf16 v[48:51], v[152:155], v[160:163], v[48:51]
	v_mfma_f32_16x16x32_bf16 v[36:39], v[144:147], v[168:171], v[36:39]
	v_mfma_f32_16x16x32_bf16 v[32:35], v[152:155], v[168:171], v[32:35]
	v_mfma_f32_16x16x32_bf16 v[20:23], v[144:147], v[192:195], v[20:23]
	v_mfma_f32_16x16x32_bf16 v[16:19], v[152:155], v[192:195], v[16:19]
	v_mfma_f32_16x16x32_bf16 v[4:7], v[144:147], v[200:203], v[4:7]
	v_mfma_f32_16x16x32_bf16 v[0:3], v[152:155], v[200:203], v[0:3]
	v_mfma_f32_16x16x32_bf16 v[52:55], v[148:151], v[164:167], v[52:55]
	v_mfma_f32_16x16x32_bf16 v[48:51], v[156:159], v[164:167], v[48:51]
	v_mfma_f32_16x16x32_bf16 v[36:39], v[148:151], v[172:175], v[36:39]
	v_mfma_f32_16x16x32_bf16 v[32:35], v[156:159], v[172:175], v[32:35]
	v_mfma_f32_16x16x32_bf16 v[20:23], v[148:151], v[196:199], v[20:23]
	v_mfma_f32_16x16x32_bf16 v[16:19], v[156:159], v[196:199], v[16:19]
	v_mfma_f32_16x16x32_bf16 v[4:7], v[148:151], v[212:215], v[4:7]
	v_mfma_f32_16x16x32_bf16 v[0:3], v[156:159], v[212:215], v[0:3]
	s_setprio 0
	s_barrier
	s_add_i32 s58, 0, 0x18000
	s_add_i32 s59, 0, 0x1c000
	v_add_u32_e32 v140, s58, v205
	v_add_u32_e32 v156, s59, v205
	ds_read_b128 v[128:131], v140
	ds_read_b128 v[132:135], v140 offset:1024
	ds_read_b128 v[136:139], v140 offset:2048
	ds_read_b128 v[140:143], v140 offset:3072
	ds_read_b128 v[144:147], v156
	ds_read_b128 v[148:151], v156 offset:1024
	ds_read_b128 v[152:155], v156 offset:2048
	ds_read_b128 v[156:159], v156 offset:3072
	s_add_u32 s44, s44, 0x40000
	s_addc_u32 s45, s45, 0
	s_mov_b32 m0, s34
	v_lshl_add_u64 v[224:225], s[44:45], 0, v[176:177]
	ds_read_b128 v[160:163], v211 offset:32768
	ds_read_b128 v[164:167], v211 offset:33792
	ds_read_b128 v[168:171], v211 offset:34816
	ds_read_b128 v[172:175], v211 offset:35840
	ds_read_b128 v[192:195], v211 offset:36864
	ds_read_b128 v[196:199], v211 offset:37888
	ds_read_b128 v[200:203], v211 offset:38912
	ds_read_b128 v[212:215], v211 offset:39936
	global_load_lds_dwordx4 v[224:225], off
	v_lshl_add_u64 v[224:225], s[44:45], 0, v[180:181]
	s_mov_b32 m0, s35
	s_nop 0
	global_load_lds_dwordx4 v[224:225], off
	s_waitcnt vmcnt(8)
	s_waitcnt lgkmcnt(0)
	s_barrier
	s_setprio 1
	s_waitcnt lgkmcnt(0)
	v_mfma_f32_16x16x32_bf16 v[124:127], v[128:131], v[160:163], v[124:127]
	v_mfma_f32_16x16x32_bf16 v[120:123], v[136:139], v[160:163], v[120:123]
	v_mfma_f32_16x16x32_bf16 v[108:111], v[128:131], v[168:171], v[108:111]
	v_mfma_f32_16x16x32_bf16 v[104:107], v[136:139], v[168:171], v[104:107]
	v_mfma_f32_16x16x32_bf16 v[92:95], v[128:131], v[192:195], v[92:95]
	v_mfma_f32_16x16x32_bf16 v[88:91], v[136:139], v[192:195], v[88:91]
	v_mfma_f32_16x16x32_bf16 v[76:79], v[128:131], v[200:203], v[76:79]
	v_mfma_f32_16x16x32_bf16 v[72:75], v[136:139], v[200:203], v[72:75]
	v_mfma_f32_16x16x32_bf16 v[124:127], v[132:135], v[164:167], v[124:127]
	v_mfma_f32_16x16x32_bf16 v[120:123], v[140:143], v[164:167], v[120:123]
	v_mfma_f32_16x16x32_bf16 v[108:111], v[132:135], v[172:175], v[108:111]
	v_mfma_f32_16x16x32_bf16 v[104:107], v[140:143], v[172:175], v[104:107]
	v_mfma_f32_16x16x32_bf16 v[92:95], v[132:135], v[196:199], v[92:95]
	v_mfma_f32_16x16x32_bf16 v[88:91], v[140:143], v[196:199], v[88:91]
	v_mfma_f32_16x16x32_bf16 v[76:79], v[132:135], v[212:215], v[76:79]
	v_mfma_f32_16x16x32_bf16 v[72:75], v[140:143], v[212:215], v[72:75]
	s_setprio 0
	s_setprio 1
	v_mfma_f32_16x16x32_bf16 v[116:119], v[144:147], v[160:163], v[116:119]
	v_mfma_f32_16x16x32_bf16 v[112:115], v[152:155], v[160:163], v[112:115]
	v_mfma_f32_16x16x32_bf16 v[100:103], v[144:147], v[168:171], v[100:103]
	v_mfma_f32_16x16x32_bf16 v[96:99], v[152:155], v[168:171], v[96:99]
	v_mfma_f32_16x16x32_bf16 v[84:87], v[144:147], v[192:195], v[84:87]
	v_mfma_f32_16x16x32_bf16 v[80:83], v[152:155], v[192:195], v[80:83]
	v_mfma_f32_16x16x32_bf16 v[68:71], v[144:147], v[200:203], v[68:71]
	v_mfma_f32_16x16x32_bf16 v[64:67], v[152:155], v[200:203], v[64:67]
	v_mfma_f32_16x16x32_bf16 v[116:119], v[148:151], v[164:167], v[116:119]
	v_mfma_f32_16x16x32_bf16 v[112:115], v[156:159], v[164:167], v[112:115]
	v_mfma_f32_16x16x32_bf16 v[100:103], v[148:151], v[172:175], v[100:103]
	v_mfma_f32_16x16x32_bf16 v[96:99], v[156:159], v[172:175], v[96:99]
	v_mfma_f32_16x16x32_bf16 v[84:87], v[148:151], v[196:199], v[84:87]
	v_mfma_f32_16x16x32_bf16 v[80:83], v[156:159], v[196:199], v[80:83]
	v_mfma_f32_16x16x32_bf16 v[68:71], v[148:151], v[212:215], v[68:71]
	v_mfma_f32_16x16x32_bf16 v[64:67], v[156:159], v[212:215], v[64:67]
	s_setprio 0
	s_barrier
	v_lshl_add_u64 v[252:253], v[220:221], 0, s[16:17]
	s_mov_b32 m0, s49
	s_nop 0
	global_load_lds_dwordx4 v[252:253], off
	v_lshl_add_u64 v[252:253], v[222:223], 0, s[16:17]
	s_mov_b32 m0, s50
	s_nop 0
	global_load_lds_dwordx4 v[252:253], off
	s_add_i32 s44, s58, s30
	v_lshl_add_u64 v[216:217], v[216:217], 0, s[16:17]
	s_mov_b32 m0, s44
	ds_read_b128 v[160:163], v211 offset:49152
	ds_read_b128 v[164:167], v211 offset:50176
	ds_read_b128 v[168:171], v211 offset:51200
	ds_read_b128 v[172:175], v211 offset:52224
	ds_read_b128 v[192:195], v211 offset:53248
	ds_read_b128 v[196:199], v211 offset:54272
	ds_read_b128 v[200:203], v211 offset:55296
	ds_read_b128 v[212:215], v211 offset:56320
	global_load_lds_dwordx4 v[216:217], off
	s_add_i32 m0, s44, 0x2000
	s_add_u32 s42, s42, 0x40080
	v_lshl_add_u64 v[216:217], v[218:219], 0, s[16:17]
	s_addc_u32 s43, s43, 0
	s_add_i32 s44, s59, s30
	global_load_lds_dwordx4 v[216:217], off
	v_lshl_add_u64 v[216:217], s[42:43], 0, v[178:179]
	s_mov_b32 m0, s44
	s_nop 0
	global_load_lds_dwordx4 v[216:217], off
	v_lshl_add_u64 v[216:217], s[42:43], 0, v[182:183]
	s_add_i32 m0, s44, 0x2000
	s_nop 0
	global_load_lds_dwordx4 v[216:217], off
	v_lshl_add_u64 v[216:217], v[220:221], 0, s[16:17]
	v_lshl_add_u64 v[216:217], v[222:223], 0, s[16:17]
	s_waitcnt vmcnt(8)
	s_waitcnt lgkmcnt(0)
	s_barrier
	s_setprio 1
	s_waitcnt lgkmcnt(0)
	v_mfma_f32_16x16x32_bf16 v[60:63], v[128:131], v[160:163], v[60:63]
	v_mfma_f32_16x16x32_bf16 v[56:59], v[136:139], v[160:163], v[56:59]
	v_mfma_f32_16x16x32_bf16 v[44:47], v[128:131], v[168:171], v[44:47]
	v_mfma_f32_16x16x32_bf16 v[40:43], v[136:139], v[168:171], v[40:43]
	v_mfma_f32_16x16x32_bf16 v[28:31], v[128:131], v[192:195], v[28:31]
	v_mfma_f32_16x16x32_bf16 v[24:27], v[136:139], v[192:195], v[24:27]
	v_mfma_f32_16x16x32_bf16 v[12:15], v[128:131], v[200:203], v[12:15]
	v_mfma_f32_16x16x32_bf16 v[8:11], v[136:139], v[200:203], v[8:11]
	v_mfma_f32_16x16x32_bf16 v[60:63], v[132:135], v[164:167], v[60:63]
	v_mfma_f32_16x16x32_bf16 v[56:59], v[140:143], v[164:167], v[56:59]
	v_mfma_f32_16x16x32_bf16 v[44:47], v[132:135], v[172:175], v[44:47]
	v_mfma_f32_16x16x32_bf16 v[40:43], v[140:143], v[172:175], v[40:43]
	v_mfma_f32_16x16x32_bf16 v[28:31], v[132:135], v[196:199], v[28:31]
	v_mfma_f32_16x16x32_bf16 v[24:27], v[140:143], v[196:199], v[24:27]
	v_mfma_f32_16x16x32_bf16 v[12:15], v[132:135], v[212:215], v[12:15]
	v_mfma_f32_16x16x32_bf16 v[8:11], v[140:143], v[212:215], v[8:11]
	s_setprio 0
	s_setprio 1
	v_mfma_f32_16x16x32_bf16 v[52:55], v[144:147], v[160:163], v[52:55]
	v_mfma_f32_16x16x32_bf16 v[48:51], v[152:155], v[160:163], v[48:51]
	v_mfma_f32_16x16x32_bf16 v[36:39], v[144:147], v[168:171], v[36:39]
	v_mfma_f32_16x16x32_bf16 v[32:35], v[152:155], v[168:171], v[32:35]
	v_mfma_f32_16x16x32_bf16 v[20:23], v[144:147], v[192:195], v[20:23]
	v_mfma_f32_16x16x32_bf16 v[16:19], v[152:155], v[192:195], v[16:19]
	v_mfma_f32_16x16x32_bf16 v[4:7], v[144:147], v[200:203], v[4:7]
	v_mfma_f32_16x16x32_bf16 v[0:3], v[152:155], v[200:203], v[0:3]
	v_mfma_f32_16x16x32_bf16 v[52:55], v[148:151], v[164:167], v[52:55]
	v_mfma_f32_16x16x32_bf16 v[48:51], v[156:159], v[164:167], v[48:51]
	v_mfma_f32_16x16x32_bf16 v[36:39], v[148:151], v[172:175], v[36:39]
	v_mfma_f32_16x16x32_bf16 v[32:35], v[156:159], v[172:175], v[32:35]
	v_mfma_f32_16x16x32_bf16 v[20:23], v[148:151], v[196:199], v[20:23]
	v_mfma_f32_16x16x32_bf16 v[16:19], v[156:159], v[196:199], v[16:19]
	v_mfma_f32_16x16x32_bf16 v[4:7], v[148:151], v[212:215], v[4:7]
	v_mfma_f32_16x16x32_bf16 v[0:3], v[156:159], v[212:215], v[0:3]
	s_setprio 0
	s_barrier
	s_add_i32 s57, s57, 2
	s_add_u32 s40, s40, 0x100
	s_addc_u32 s41, s41, 0
	s_add_u32 s55, s55, 0x100
	s_addc_u32 s56, s56, 0
	s_cmp_gt_u32 s57, 13
	s_cbranch_scc0 .LBB5_536
	s_nop 0
	s_nop 0
	s_nop 0
	s_nop 0
	s_nop 0
	s_nop 0
	s_nop 0
	s_nop 0
	s_nop 0
	s_nop 0
	s_nop 0
	s_nop 0
	s_nop 0
	s_nop 0
	s_nop 0
	s_nop 0
	s_nop 0
	s_nop 0
	s_nop 0
	s_nop 0
	s_nop 0
	s_nop 0
	s_and_b64 vcc, exec, s[14:15]
	s_cbranch_vccz .LBB5_539
	s_barrier

.Lskw_P5:
	s_waitcnt lgkmcnt(0)
	s_barrier
	s_setprio 1
	s_waitcnt lgkmcnt(0)
	v_mfma_f32_16x16x32_bf16 v[140:143], v[32:35], v[192:195], v[140:143]
	v_mfma_f32_16x16x32_bf16 v[136:139], v[40:43], v[192:195], v[136:139]
	v_mfma_f32_16x16x32_bf16 v[124:127], v[32:35], v[200:203], v[124:127]
	v_mfma_f32_16x16x32_bf16 v[120:123], v[40:43], v[200:203], v[120:123]
	v_mfma_f32_16x16x32_bf16 v[108:111], v[32:35], v[208:211], v[108:111]
	v_mfma_f32_16x16x32_bf16 v[104:107], v[40:43], v[208:211], v[104:107]
	v_mfma_f32_16x16x32_bf16 v[92:95], v[32:35], v[216:219], v[92:95]
	v_mfma_f32_16x16x32_bf16 v[88:91], v[40:43], v[216:219], v[88:91]
	v_mfma_f32_16x16x32_bf16 v[140:143], v[36:39], v[196:199], v[140:143]
	v_mfma_f32_16x16x32_bf16 v[136:139], v[44:47], v[196:199], v[136:139]
	v_mfma_f32_16x16x32_bf16 v[124:127], v[36:39], v[204:207], v[124:127]
	v_mfma_f32_16x16x32_bf16 v[120:123], v[44:47], v[204:207], v[120:123]
	v_mfma_f32_16x16x32_bf16 v[108:111], v[36:39], v[212:215], v[108:111]
	v_mfma_f32_16x16x32_bf16 v[104:107], v[44:47], v[212:215], v[104:107]
	v_mfma_f32_16x16x32_bf16 v[92:95], v[36:39], v[220:223], v[92:95]
	v_mfma_f32_16x16x32_bf16 v[88:91], v[44:47], v[220:223], v[88:91]
	s_setprio 0
	s_setprio 1
	v_mfma_f32_16x16x32_bf16 v[132:135], v[144:147], v[192:195], v[132:135]
	v_mfma_f32_16x16x32_bf16 v[128:131], v[152:155], v[192:195], v[128:131]
	v_mfma_f32_16x16x32_bf16 v[116:119], v[144:147], v[200:203], v[116:119]
	v_mfma_f32_16x16x32_bf16 v[112:115], v[152:155], v[200:203], v[112:115]
	v_mfma_f32_16x16x32_bf16 v[100:103], v[144:147], v[208:211], v[100:103]
	v_mfma_f32_16x16x32_bf16 v[96:99], v[152:155], v[208:211], v[96:99]
	v_mfma_f32_16x16x32_bf16 v[84:87], v[144:147], v[216:219], v[84:87]
	v_mfma_f32_16x16x32_bf16 v[80:83], v[152:155], v[216:219], v[80:83]
	v_mfma_f32_16x16x32_bf16 v[132:135], v[148:151], v[196:199], v[132:135]
	v_mfma_f32_16x16x32_bf16 v[128:131], v[156:159], v[196:199], v[128:131]
	v_mfma_f32_16x16x32_bf16 v[116:119], v[148:151], v[204:207], v[116:119]
	v_mfma_f32_16x16x32_bf16 v[112:115], v[156:159], v[204:207], v[112:115]
	v_mfma_f32_16x16x32_bf16 v[100:103], v[148:151], v[212:215], v[100:103]
	v_mfma_f32_16x16x32_bf16 v[96:99], v[156:159], v[212:215], v[96:99]
	v_mfma_f32_16x16x32_bf16 v[84:87], v[148:151], v[220:223], v[84:87]
	v_mfma_f32_16x16x32_bf16 v[80:83], v[156:159], v[220:223], v[80:83]
	s_setprio 0
	s_barrier
	v_lshl_add_u64 v[252:253], s[56:57], 0, v[160:161]
	s_mov_b32 m0, s61
	s_nop 0
	global_load_lds_dwordx4 v[252:253], off
	v_lshl_add_u64 v[252:253], s[56:57], 0, v[164:165]
	s_mov_b32 m0, s62
	s_nop 0
	global_load_lds_dwordx4 v[252:253], off
	s_add_i32 s34, s80, s60
	v_lshl_add_u64 v[180:181], s[8:9], 0, v[162:163]
	s_mov_b32 m0, s34
	ds_read_b128 v[192:195], v188 offset:16384
	ds_read_b128 v[196:199], v188 offset:17408
	ds_read_b128 v[200:203], v188 offset:18432
	ds_read_b128 v[204:207], v188 offset:19456
	ds_read_b128 v[208:211], v188 offset:20480
	ds_read_b128 v[212:215], v188 offset:21504
	ds_read_b128 v[216:219], v188 offset:22528
	ds_read_b128 v[220:223], v188 offset:23552
	global_load_lds_dwordx4 v[180:181], off
	s_add_i32 m0, s34, 0x2000
	s_add_u32 s34, s8, 0x40000
	v_lshl_add_u64 v[224:225], s[8:9], 0, v[166:167]
	s_addc_u32 s35, s9, 0
	s_add_i32 s49, s81, s60
	global_load_lds_dwordx4 v[224:225], off
	v_lshl_add_u64 v[226:227], s[34:35], 0, v[162:163]
	s_mov_b32 m0, s49
	v_lshl_add_u64 v[228:229], s[56:57], 0, v[164:165]
	global_load_lds_dwordx4 v[226:227], off
	v_lshl_add_u64 v[226:227], s[34:35], 0, v[166:167]
	s_add_i32 m0, s49, 0x2000
	s_nop 0
	global_load_lds_dwordx4 v[226:227], off
	v_lshl_add_u64 v[226:227], s[56:57], 0, v[160:161]
	s_waitcnt vmcnt(8)
	s_waitcnt lgkmcnt(0)
	s_barrier
	s_setprio 1
	s_waitcnt lgkmcnt(0)
	v_mfma_f32_16x16x32_bf16 v[76:79], v[32:35], v[192:195], v[76:79]
	v_mfma_f32_16x16x32_bf16 v[72:75], v[40:43], v[192:195], v[72:75]
	v_mfma_f32_16x16x32_bf16 v[60:63], v[32:35], v[200:203], v[60:63]
	v_mfma_f32_16x16x32_bf16 v[56:59], v[40:43], v[200:203], v[56:59]
	v_mfma_f32_16x16x32_bf16 v[28:31], v[32:35], v[208:211], v[28:31]
	v_mfma_f32_16x16x32_bf16 v[24:27], v[40:43], v[208:211], v[24:27]
	v_mfma_f32_16x16x32_bf16 v[12:15], v[32:35], v[216:219], v[12:15]
	v_mfma_f32_16x16x32_bf16 v[8:11], v[40:43], v[216:219], v[8:11]
	v_mfma_f32_16x16x32_bf16 v[76:79], v[36:39], v[196:199], v[76:79]
	v_mfma_f32_16x16x32_bf16 v[72:75], v[44:47], v[196:199], v[72:75]
	v_mfma_f32_16x16x32_bf16 v[60:63], v[36:39], v[204:207], v[60:63]
	v_mfma_f32_16x16x32_bf16 v[56:59], v[44:47], v[204:207], v[56:59]
	v_mfma_f32_16x16x32_bf16 v[28:31], v[36:39], v[212:215], v[28:31]
	v_mfma_f32_16x16x32_bf16 v[24:27], v[44:47], v[212:215], v[24:27]
	v_mfma_f32_16x16x32_bf16 v[12:15], v[36:39], v[220:223], v[12:15]
	v_mfma_f32_16x16x32_bf16 v[8:11], v[44:47], v[220:223], v[8:11]
	s_setprio 0
	s_setprio 1
	v_mfma_f32_16x16x32_bf16 v[20:23], v[144:147], v[208:211], v[20:23]
	v_mfma_f32_16x16x32_bf16 v[16:19], v[152:155], v[208:211], v[16:19]
	v_mfma_f32_16x16x32_bf16 v[4:7], v[144:147], v[216:219], v[4:7]
	v_mfma_f32_16x16x32_bf16 v[0:3], v[152:155], v[216:219], v[0:3]
	v_mfma_f32_16x16x32_bf16 v[32:35], v[144:147], v[192:195], v[68:71]
	v_mfma_f32_16x16x32_bf16 v[36:39], v[152:155], v[192:195], v[64:67]
	v_mfma_f32_16x16x32_bf16 v[40:43], v[144:147], v[200:203], v[52:55]
	v_mfma_f32_16x16x32_bf16 v[44:47], v[152:155], v[200:203], v[48:51]
	v_mfma_f32_16x16x32_bf16 v[20:23], v[148:151], v[212:215], v[20:23]
	v_mfma_f32_16x16x32_bf16 v[16:19], v[156:159], v[212:215], v[16:19]
	v_mfma_f32_16x16x32_bf16 v[4:7], v[148:151], v[220:223], v[4:7]
	v_mfma_f32_16x16x32_bf16 v[0:3], v[156:159], v[220:223], v[0:3]
	v_mfma_f32_16x16x32_bf16 v[32:35], v[148:151], v[196:199], v[32:35]
	v_mfma_f32_16x16x32_bf16 v[36:39], v[156:159], v[196:199], v[36:39]
	v_mfma_f32_16x16x32_bf16 v[40:43], v[148:151], v[204:207], v[40:43]
	v_mfma_f32_16x16x32_bf16 v[44:47], v[156:159], v[204:207], v[44:47]
	s_setprio 0
	s_barrier
	s_add_i32 s49, 0, 0x18000
	s_add_i32 s51, 0, 0x1c000
	v_add_u32_e32 v68, s49, v183
	v_add_u32_e32 v156, s51, v183
	ds_read_b128 v[48:51], v68
	ds_read_b128 v[52:55], v68 offset:1024
	ds_read_b128 v[64:67], v68 offset:2048
	ds_read_b128 v[68:71], v68 offset:3072
	ds_read_b128 v[144:147], v156
	ds_read_b128 v[148:151], v156 offset:1024
	ds_read_b128 v[152:155], v156 offset:2048
	ds_read_b128 v[156:159], v156 offset:3072
	s_add_u32 s34, s56, 0x40000
	s_addc_u32 s35, s57, 0
	s_mov_b32 m0, s63
	v_lshl_add_u64 v[230:231], s[34:35], 0, v[160:161]
	ds_read_b128 v[192:195], v188 offset:32768
	ds_read_b128 v[196:199], v188 offset:33792
	ds_read_b128 v[200:203], v188 offset:34816
	ds_read_b128 v[204:207], v188 offset:35840
	ds_read_b128 v[208:211], v188 offset:36864
	ds_read_b128 v[212:215], v188 offset:37888
	ds_read_b128 v[216:219], v188 offset:38912
	ds_read_b128 v[220:223], v188 offset:39936
	global_load_lds_dwordx4 v[230:231], off
	v_lshl_add_u64 v[230:231], s[34:35], 0, v[164:165]
	s_mov_b32 m0, s64
	s_nop 0
	global_load_lds_dwordx4 v[230:231], off
	s_waitcnt vmcnt(8)
	s_waitcnt lgkmcnt(0)
	s_barrier
	s_setprio 1
	s_waitcnt lgkmcnt(0)
	v_mfma_f32_16x16x32_bf16 v[140:143], v[48:51], v[192:195], v[140:143]
	v_mfma_f32_16x16x32_bf16 v[136:139], v[64:67], v[192:195], v[136:139]
	v_mfma_f32_16x16x32_bf16 v[124:127], v[48:51], v[200:203], v[124:127]
	v_mfma_f32_16x16x32_bf16 v[120:123], v[64:67], v[200:203], v[120:123]
	v_mfma_f32_16x16x32_bf16 v[108:111], v[48:51], v[208:211], v[108:111]
	v_mfma_f32_16x16x32_bf16 v[104:107], v[64:67], v[208:211], v[104:107]
	v_mfma_f32_16x16x32_bf16 v[92:95], v[48:51], v[216:219], v[92:95]
	v_mfma_f32_16x16x32_bf16 v[88:91], v[64:67], v[216:219], v[88:91]
	v_mfma_f32_16x16x32_bf16 v[140:143], v[52:55], v[196:199], v[140:143]
	v_mfma_f32_16x16x32_bf16 v[136:139], v[68:71], v[196:199], v[136:139]
	v_mfma_f32_16x16x32_bf16 v[124:127], v[52:55], v[204:207], v[124:127]
	v_mfma_f32_16x16x32_bf16 v[120:123], v[68:71], v[204:207], v[120:123]
	v_mfma_f32_16x16x32_bf16 v[108:111], v[52:55], v[212:215], v[108:111]
	v_mfma_f32_16x16x32_bf16 v[104:107], v[68:71], v[212:215], v[104:107]
	v_mfma_f32_16x16x32_bf16 v[92:95], v[52:55], v[220:223], v[92:95]
	v_mfma_f32_16x16x32_bf16 v[88:91], v[68:71], v[220:223], v[88:91]
	s_setprio 0
	s_setprio 1
	v_mfma_f32_16x16x32_bf16 v[132:135], v[144:147], v[192:195], v[132:135]
	v_mfma_f32_16x16x32_bf16 v[128:131], v[152:155], v[192:195], v[128:131]
	v_mfma_f32_16x16x32_bf16 v[116:119], v[144:147], v[200:203], v[116:119]
	v_mfma_f32_16x16x32_bf16 v[112:115], v[152:155], v[200:203], v[112:115]
	v_mfma_f32_16x16x32_bf16 v[100:103], v[144:147], v[208:211], v[100:103]
	v_mfma_f32_16x16x32_bf16 v[96:99], v[152:155], v[208:211], v[96:99]
	v_mfma_f32_16x16x32_bf16 v[84:87], v[144:147], v[216:219], v[84:87]
	v_mfma_f32_16x16x32_bf16 v[80:83], v[152:155], v[216:219], v[80:83]
	v_mfma_f32_16x16x32_bf16 v[132:135], v[148:151], v[196:199], v[132:135]
	v_mfma_f32_16x16x32_bf16 v[128:131], v[156:159], v[196:199], v[128:131]
	v_mfma_f32_16x16x32_bf16 v[116:119], v[148:151], v[204:207], v[116:119]
	v_mfma_f32_16x16x32_bf16 v[112:115], v[156:159], v[204:207], v[112:115]
	v_mfma_f32_16x16x32_bf16 v[100:103], v[148:151], v[212:215], v[100:103]
	v_mfma_f32_16x16x32_bf16 v[96:99], v[156:159], v[212:215], v[96:99]
	v_mfma_f32_16x16x32_bf16 v[84:87], v[148:151], v[220:223], v[84:87]
	v_mfma_f32_16x16x32_bf16 v[80:83], v[156:159], v[220:223], v[80:83]
	s_setprio 0
	s_barrier
	v_lshl_add_u64 v[252:253], v[226:227], 0, s[46:47]
	s_mov_b32 m0, s78
	s_nop 0
	global_load_lds_dwordx4 v[252:253], off
	v_lshl_add_u64 v[252:253], v[228:229], 0, s[46:47]
	s_mov_b32 m0, s79
	s_nop 0
	global_load_lds_dwordx4 v[252:253], off
	s_add_i32 s34, s49, s60
	v_lshl_add_u64 v[180:181], v[180:181], 0, s[46:47]
	s_mov_b32 m0, s34
	ds_read_b128 v[192:195], v188 offset:49152
	ds_read_b128 v[196:199], v188 offset:50176
	ds_read_b128 v[200:203], v188 offset:51200
	ds_read_b128 v[204:207], v188 offset:52224
	ds_read_b128 v[208:211], v188 offset:53248
	ds_read_b128 v[212:215], v188 offset:54272
	ds_read_b128 v[216:219], v188 offset:55296
	ds_read_b128 v[220:223], v188 offset:56320
	global_load_lds_dwordx4 v[180:181], off
	s_add_i32 m0, s34, 0x2000
	s_add_u32 s8, s8, 0x40080
	v_lshl_add_u64 v[180:181], v[224:225], 0, s[46:47]
	s_addc_u32 s9, s9, 0
	s_add_i32 s34, s51, s60
	global_load_lds_dwordx4 v[180:181], off
	v_lshl_add_u64 v[180:181], s[8:9], 0, v[162:163]
	s_mov_b32 m0, s34
	s_nop 0
	global_load_lds_dwordx4 v[180:181], off
	v_lshl_add_u64 v[180:181], s[8:9], 0, v[166:167]
	s_add_i32 m0, s34, 0x2000
	s_nop 0
	global_load_lds_dwordx4 v[180:181], off
	v_lshl_add_u64 v[180:181], v[226:227], 0, s[46:47]
	v_lshl_add_u64 v[180:181], v[228:229], 0, s[46:47]
	s_waitcnt vmcnt(8)
	s_waitcnt lgkmcnt(0)
	s_barrier
	s_setprio 1
	s_waitcnt lgkmcnt(0)
	v_mfma_f32_16x16x32_bf16 v[76:79], v[48:51], v[192:195], v[76:79]
	v_mfma_f32_16x16x32_bf16 v[72:75], v[64:67], v[192:195], v[72:75]
	v_mfma_f32_16x16x32_bf16 v[60:63], v[48:51], v[200:203], v[60:63]
	v_mfma_f32_16x16x32_bf16 v[56:59], v[64:67], v[200:203], v[56:59]
	v_mfma_f32_16x16x32_bf16 v[28:31], v[48:51], v[208:211], v[28:31]
	v_mfma_f32_16x16x32_bf16 v[24:27], v[64:67], v[208:211], v[24:27]
	v_mfma_f32_16x16x32_bf16 v[12:15], v[48:51], v[216:219], v[12:15]
	v_mfma_f32_16x16x32_bf16 v[8:11], v[64:67], v[216:219], v[8:11]
	v_mfma_f32_16x16x32_bf16 v[76:79], v[52:55], v[196:199], v[76:79]
	v_mfma_f32_16x16x32_bf16 v[72:75], v[68:71], v[196:199], v[72:75]
	v_mfma_f32_16x16x32_bf16 v[60:63], v[52:55], v[204:207], v[60:63]
	v_mfma_f32_16x16x32_bf16 v[56:59], v[68:71], v[204:207], v[56:59]
	v_mfma_f32_16x16x32_bf16 v[28:31], v[52:55], v[212:215], v[28:31]
	v_mfma_f32_16x16x32_bf16 v[24:27], v[68:71], v[212:215], v[24:27]
	v_mfma_f32_16x16x32_bf16 v[12:15], v[52:55], v[220:223], v[12:15]
	v_mfma_f32_16x16x32_bf16 v[8:11], v[68:71], v[220:223], v[8:11]
	s_setprio 0
	s_setprio 1
	v_mfma_f32_16x16x32_bf16 v[32:35], v[144:147], v[192:195], v[32:35]
	v_mfma_f32_16x16x32_bf16 v[68:71], v[148:151], v[196:199], v[32:35]
	v_mfma_f32_16x16x32_bf16 v[32:35], v[152:155], v[192:195], v[36:39]
	v_mfma_f32_16x16x32_bf16 v[64:67], v[156:159], v[196:199], v[32:35]
	v_mfma_f32_16x16x32_bf16 v[32:35], v[144:147], v[200:203], v[40:43]
	v_mfma_f32_16x16x32_bf16 v[52:55], v[148:151], v[204:207], v[32:35]
	v_mfma_f32_16x16x32_bf16 v[32:35], v[152:155], v[200:203], v[44:47]
	v_mfma_f32_16x16x32_bf16 v[20:23], v[144:147], v[208:211], v[20:23]
	v_mfma_f32_16x16x32_bf16 v[16:19], v[152:155], v[208:211], v[16:19]
	v_mfma_f32_16x16x32_bf16 v[4:7], v[144:147], v[216:219], v[4:7]
	v_mfma_f32_16x16x32_bf16 v[0:3], v[152:155], v[216:219], v[0:3]
	v_mfma_f32_16x16x32_bf16 v[48:51], v[156:159], v[204:207], v[32:35]
	v_mfma_f32_16x16x32_bf16 v[20:23], v[148:151], v[212:215], v[20:23]
	v_mfma_f32_16x16x32_bf16 v[16:19], v[156:159], v[212:215], v[16:19]
	v_mfma_f32_16x16x32_bf16 v[4:7], v[148:151], v[220:223], v[4:7]
	v_mfma_f32_16x16x32_bf16 v[0:3], v[156:159], v[220:223], v[0:3]
	s_setprio 0
	s_barrier
	s_add_i32 s33, s33, 2
	s_add_u32 s6, s6, 0x100
	s_addc_u32 s7, s7, 0
	s_add_u32 s25, s25, 0x100
	s_addc_u32 s30, s30, 0
	s_cmp_gt_u32 s33, 13
	s_cbranch_scc0 .LBB5_625
	s_nop 0
	s_nop 0
	s_nop 0
	s_nop 0
	s_nop 0
	s_nop 0
	s_nop 0
	s_nop 0
	s_nop 0
	s_nop 0
	s_nop 0
	s_nop 0
	s_nop 0
	s_nop 0
	s_nop 0
	s_nop 0
	s_nop 0
	s_nop 0
	s_nop 0
	s_nop 0
	s_nop 0
	s_nop 0
	s_and_b64 vcc, exec, s[42:43]
	s_cbranch_vccz .LBB5_628
	s_barrier

.Lskw_P8:
	s_waitcnt lgkmcnt(0)
	s_barrier
	s_setprio 1
	s_waitcnt lgkmcnt(0)
	v_mfma_f32_16x16x32_bf16 v[124:127], v[128:131], v[176:179], v[124:127]
	v_mfma_f32_16x16x32_bf16 v[120:123], v[136:139], v[176:179], v[120:123]
	v_mfma_f32_16x16x32_bf16 v[108:111], v[128:131], v[194:197], v[108:111]
	v_mfma_f32_16x16x32_bf16 v[104:107], v[136:139], v[194:197], v[104:107]
	v_mfma_f32_16x16x32_bf16 v[92:95], v[128:131], v[202:205], v[92:95]
	v_mfma_f32_16x16x32_bf16 v[88:91], v[136:139], v[202:205], v[88:91]
	v_mfma_f32_16x16x32_bf16 v[76:79], v[128:131], v[210:213], v[76:79]
	v_mfma_f32_16x16x32_bf16 v[72:75], v[136:139], v[210:213], v[72:75]
	v_mfma_f32_16x16x32_bf16 v[124:127], v[132:135], v[180:183], v[124:127]
	v_mfma_f32_16x16x32_bf16 v[120:123], v[140:143], v[180:183], v[120:123]
	v_mfma_f32_16x16x32_bf16 v[108:111], v[132:135], v[198:201], v[108:111]
	v_mfma_f32_16x16x32_bf16 v[104:107], v[140:143], v[198:201], v[104:107]
	v_mfma_f32_16x16x32_bf16 v[92:95], v[132:135], v[206:209], v[92:95]
	v_mfma_f32_16x16x32_bf16 v[88:91], v[140:143], v[206:209], v[88:91]
	v_mfma_f32_16x16x32_bf16 v[76:79], v[132:135], v[214:217], v[76:79]
	v_mfma_f32_16x16x32_bf16 v[72:75], v[140:143], v[214:217], v[72:75]
	s_setprio 0
	s_setprio 1
	v_mfma_f32_16x16x32_bf16 v[116:119], v[144:147], v[176:179], v[116:119]
	v_mfma_f32_16x16x32_bf16 v[112:115], v[168:171], v[176:179], v[112:115]
	v_mfma_f32_16x16x32_bf16 v[100:103], v[144:147], v[194:197], v[100:103]
	v_mfma_f32_16x16x32_bf16 v[96:99], v[168:171], v[194:197], v[96:99]
	v_mfma_f32_16x16x32_bf16 v[84:87], v[144:147], v[202:205], v[84:87]
	v_mfma_f32_16x16x32_bf16 v[80:83], v[168:171], v[202:205], v[80:83]
	v_mfma_f32_16x16x32_bf16 v[68:71], v[144:147], v[210:213], v[68:71]
	v_mfma_f32_16x16x32_bf16 v[64:67], v[168:171], v[210:213], v[64:67]
	v_mfma_f32_16x16x32_bf16 v[116:119], v[148:151], v[180:183], v[116:119]
	v_mfma_f32_16x16x32_bf16 v[112:115], v[172:175], v[180:183], v[112:115]
	v_mfma_f32_16x16x32_bf16 v[100:103], v[148:151], v[198:201], v[100:103]
	v_mfma_f32_16x16x32_bf16 v[96:99], v[172:175], v[198:201], v[96:99]
	v_mfma_f32_16x16x32_bf16 v[84:87], v[148:151], v[206:209], v[84:87]
	v_mfma_f32_16x16x32_bf16 v[80:83], v[172:175], v[206:209], v[80:83]
	v_mfma_f32_16x16x32_bf16 v[68:71], v[148:151], v[214:217], v[68:71]
	v_mfma_f32_16x16x32_bf16 v[64:67], v[172:175], v[214:217], v[64:67]
	s_setprio 0
	s_barrier
	v_lshl_add_u64 v[252:253], s[42:43], 0, v[152:153]
	s_mov_b32 m0, s34
	s_nop 0
	global_load_lds_dwordx4 v[252:253], off
	v_lshl_add_u64 v[252:253], s[42:43], 0, v[156:157]
	s_mov_b32 m0, s35
	s_nop 0
	global_load_lds_dwordx4 v[252:253], off
	s_add_i32 s58, s51, s33
	v_lshl_add_u64 v[184:185], s[40:41], 0, v[154:155]
	s_mov_b32 m0, s58
	ds_read_b128 v[176:179], v193 offset:16384
	ds_read_b128 v[180:183], v193 offset:17408
	ds_read_b128 v[194:197], v193 offset:18432
	ds_read_b128 v[198:201], v193 offset:19456
	ds_read_b128 v[202:205], v193 offset:20480
	ds_read_b128 v[206:209], v193 offset:21504
	ds_read_b128 v[210:213], v193 offset:22528
	ds_read_b128 v[214:217], v193 offset:23552
	global_load_lds_dwordx4 v[184:185], off
	s_add_i32 m0, s58, 0x2000
	s_add_u32 s58, s40, 0x40000
	v_lshl_add_u64 v[218:219], s[40:41], 0, v[158:159]
	s_addc_u32 s59, s41, 0
	s_add_i32 s60, s52, s33
	global_load_lds_dwordx4 v[218:219], off
	v_lshl_add_u64 v[220:221], s[58:59], 0, v[154:155]
	s_mov_b32 m0, s60
	v_lshl_add_u64 v[222:223], s[42:43], 0, v[156:157]
	global_load_lds_dwordx4 v[220:221], off
	v_lshl_add_u64 v[220:221], s[58:59], 0, v[158:159]
	s_add_i32 m0, s60, 0x2000
	s_nop 0
	global_load_lds_dwordx4 v[220:221], off
	v_lshl_add_u64 v[220:221], s[42:43], 0, v[152:153]
	s_waitcnt vmcnt(8)
	s_waitcnt lgkmcnt(0)
	s_barrier
	s_setprio 1
	s_waitcnt lgkmcnt(0)
	v_mfma_f32_16x16x32_bf16 v[60:63], v[128:131], v[176:179], v[60:63]
	v_mfma_f32_16x16x32_bf16 v[56:59], v[136:139], v[176:179], v[56:59]
	v_mfma_f32_16x16x32_bf16 v[44:47], v[128:131], v[194:197], v[44:47]
	v_mfma_f32_16x16x32_bf16 v[40:43], v[136:139], v[194:197], v[40:43]
	v_mfma_f32_16x16x32_bf16 v[28:31], v[128:131], v[202:205], v[28:31]
	v_mfma_f32_16x16x32_bf16 v[24:27], v[136:139], v[202:205], v[24:27]
	v_mfma_f32_16x16x32_bf16 v[12:15], v[128:131], v[210:213], v[12:15]
	v_mfma_f32_16x16x32_bf16 v[8:11], v[136:139], v[210:213], v[8:11]
	v_mfma_f32_16x16x32_bf16 v[60:63], v[132:135], v[180:183], v[60:63]
	v_mfma_f32_16x16x32_bf16 v[56:59], v[140:143], v[180:183], v[56:59]
	v_mfma_f32_16x16x32_bf16 v[44:47], v[132:135], v[198:201], v[44:47]
	v_mfma_f32_16x16x32_bf16 v[40:43], v[140:143], v[198:201], v[40:43]
	v_mfma_f32_16x16x32_bf16 v[28:31], v[132:135], v[206:209], v[28:31]
	v_mfma_f32_16x16x32_bf16 v[24:27], v[140:143], v[206:209], v[24:27]
	v_mfma_f32_16x16x32_bf16 v[12:15], v[132:135], v[214:217], v[12:15]
	v_mfma_f32_16x16x32_bf16 v[8:11], v[140:143], v[214:217], v[8:11]
	s_setprio 0
	s_setprio 1
	v_mfma_f32_16x16x32_bf16 v[52:55], v[144:147], v[176:179], v[52:55]
	v_mfma_f32_16x16x32_bf16 v[48:51], v[168:171], v[176:179], v[48:51]
	v_mfma_f32_16x16x32_bf16 v[36:39], v[144:147], v[194:197], v[36:39]
	v_mfma_f32_16x16x32_bf16 v[32:35], v[168:171], v[194:197], v[32:35]
	v_mfma_f32_16x16x32_bf16 v[20:23], v[144:147], v[202:205], v[20:23]
	v_mfma_f32_16x16x32_bf16 v[16:19], v[168:171], v[202:205], v[16:19]
	v_mfma_f32_16x16x32_bf16 v[4:7], v[144:147], v[210:213], v[4:7]
	v_mfma_f32_16x16x32_bf16 v[0:3], v[168:171], v[210:213], v[0:3]
	v_mfma_f32_16x16x32_bf16 v[52:55], v[148:151], v[180:183], v[52:55]
	v_mfma_f32_16x16x32_bf16 v[48:51], v[172:175], v[180:183], v[48:51]
	v_mfma_f32_16x16x32_bf16 v[36:39], v[148:151], v[198:201], v[36:39]
	v_mfma_f32_16x16x32_bf16 v[32:35], v[172:175], v[198:201], v[32:35]
	v_mfma_f32_16x16x32_bf16 v[20:23], v[148:151], v[206:209], v[20:23]
	v_mfma_f32_16x16x32_bf16 v[16:19], v[172:175], v[206:209], v[16:19]
	v_mfma_f32_16x16x32_bf16 v[4:7], v[148:151], v[214:217], v[4:7]
	v_mfma_f32_16x16x32_bf16 v[0:3], v[172:175], v[214:217], v[0:3]
	s_setprio 0
	s_barrier
	s_add_i32 s58, 0, 0x18000
	s_add_i32 s59, 0, 0x1c000
	v_add_u32_e32 v140, s58, v187
	v_add_u32_e32 v172, s59, v187
	ds_read_b128 v[128:131], v140
	ds_read_b128 v[132:135], v140 offset:1024
	ds_read_b128 v[136:139], v140 offset:2048
	ds_read_b128 v[140:143], v140 offset:3072
	ds_read_b128 v[144:147], v172
	ds_read_b128 v[148:151], v172 offset:1024
	ds_read_b128 v[168:171], v172 offset:2048
	ds_read_b128 v[172:175], v172 offset:3072
	s_add_u32 s42, s42, 0x40000
	s_addc_u32 s43, s43, 0
	s_mov_b32 m0, s44
	v_lshl_add_u64 v[224:225], s[42:43], 0, v[152:153]
	ds_read_b128 v[176:179], v193 offset:32768
	ds_read_b128 v[180:183], v193 offset:33792
	ds_read_b128 v[194:197], v193 offset:34816
	ds_read_b128 v[198:201], v193 offset:35840
	ds_read_b128 v[202:205], v193 offset:36864
	ds_read_b128 v[206:209], v193 offset:37888
	ds_read_b128 v[210:213], v193 offset:38912
	ds_read_b128 v[214:217], v193 offset:39936
	global_load_lds_dwordx4 v[224:225], off
	v_lshl_add_u64 v[224:225], s[42:43], 0, v[156:157]
	s_mov_b32 m0, s45
	s_nop 0
	global_load_lds_dwordx4 v[224:225], off
	s_waitcnt vmcnt(8)
	s_waitcnt lgkmcnt(0)
	s_barrier
	s_setprio 1
	s_waitcnt lgkmcnt(0)
	v_mfma_f32_16x16x32_bf16 v[124:127], v[128:131], v[176:179], v[124:127]
	v_mfma_f32_16x16x32_bf16 v[120:123], v[136:139], v[176:179], v[120:123]
	v_mfma_f32_16x16x32_bf16 v[108:111], v[128:131], v[194:197], v[108:111]
	v_mfma_f32_16x16x32_bf16 v[104:107], v[136:139], v[194:197], v[104:107]
	v_mfma_f32_16x16x32_bf16 v[92:95], v[128:131], v[202:205], v[92:95]
	v_mfma_f32_16x16x32_bf16 v[88:91], v[136:139], v[202:205], v[88:91]
	v_mfma_f32_16x16x32_bf16 v[76:79], v[128:131], v[210:213], v[76:79]
	v_mfma_f32_16x16x32_bf16 v[72:75], v[136:139], v[210:213], v[72:75]
	v_mfma_f32_16x16x32_bf16 v[124:127], v[132:135], v[180:183], v[124:127]
	v_mfma_f32_16x16x32_bf16 v[120:123], v[140:143], v[180:183], v[120:123]
	v_mfma_f32_16x16x32_bf16 v[108:111], v[132:135], v[198:201], v[108:111]
	v_mfma_f32_16x16x32_bf16 v[104:107], v[140:143], v[198:201], v[104:107]
	v_mfma_f32_16x16x32_bf16 v[92:95], v[132:135], v[206:209], v[92:95]
	v_mfma_f32_16x16x32_bf16 v[88:91], v[140:143], v[206:209], v[88:91]
	v_mfma_f32_16x16x32_bf16 v[76:79], v[132:135], v[214:217], v[76:79]
	v_mfma_f32_16x16x32_bf16 v[72:75], v[140:143], v[214:217], v[72:75]
	s_setprio 0
	s_setprio 1
	v_mfma_f32_16x16x32_bf16 v[116:119], v[144:147], v[176:179], v[116:119]
	v_mfma_f32_16x16x32_bf16 v[112:115], v[168:171], v[176:179], v[112:115]
	v_mfma_f32_16x16x32_bf16 v[100:103], v[144:147], v[194:197], v[100:103]
	v_mfma_f32_16x16x32_bf16 v[96:99], v[168:171], v[194:197], v[96:99]
	v_mfma_f32_16x16x32_bf16 v[84:87], v[144:147], v[202:205], v[84:87]
	v_mfma_f32_16x16x32_bf16 v[80:83], v[168:171], v[202:205], v[80:83]
	v_mfma_f32_16x16x32_bf16 v[68:71], v[144:147], v[210:213], v[68:71]
	v_mfma_f32_16x16x32_bf16 v[64:67], v[168:171], v[210:213], v[64:67]
	v_mfma_f32_16x16x32_bf16 v[116:119], v[148:151], v[180:183], v[116:119]
	v_mfma_f32_16x16x32_bf16 v[112:115], v[172:175], v[180:183], v[112:115]
	v_mfma_f32_16x16x32_bf16 v[100:103], v[148:151], v[198:201], v[100:103]
	v_mfma_f32_16x16x32_bf16 v[96:99], v[172:175], v[198:201], v[96:99]
	v_mfma_f32_16x16x32_bf16 v[84:87], v[148:151], v[206:209], v[84:87]
	v_mfma_f32_16x16x32_bf16 v[80:83], v[172:175], v[206:209], v[80:83]
	v_mfma_f32_16x16x32_bf16 v[68:71], v[148:151], v[214:217], v[68:71]
	v_mfma_f32_16x16x32_bf16 v[64:67], v[172:175], v[214:217], v[64:67]
	s_setprio 0
	s_barrier
	v_lshl_add_u64 v[252:253], v[220:221], 0, s[18:19]
	s_mov_b32 m0, s49
	s_nop 0
	global_load_lds_dwordx4 v[252:253], off
	v_lshl_add_u64 v[252:253], v[222:223], 0, s[18:19]
	s_mov_b32 m0, s50
	s_nop 0
	global_load_lds_dwordx4 v[252:253], off
	s_add_i32 s42, s58, s33
	v_lshl_add_u64 v[184:185], v[184:185], 0, s[18:19]
	s_mov_b32 m0, s42
	ds_read_b128 v[176:179], v193 offset:49152
	ds_read_b128 v[180:183], v193 offset:50176
	ds_read_b128 v[194:197], v193 offset:51200
	ds_read_b128 v[198:201], v193 offset:52224
	ds_read_b128 v[202:205], v193 offset:53248
	ds_read_b128 v[206:209], v193 offset:54272
	ds_read_b128 v[210:213], v193 offset:55296
	ds_read_b128 v[214:217], v193 offset:56320
	global_load_lds_dwordx4 v[184:185], off
	s_add_i32 m0, s42, 0x2000
	s_add_u32 s40, s40, 0x40080
	v_lshl_add_u64 v[184:185], v[218:219], 0, s[18:19]
	s_addc_u32 s41, s41, 0
	s_add_i32 s42, s59, s33
	global_load_lds_dwordx4 v[184:185], off
	v_lshl_add_u64 v[184:185], s[40:41], 0, v[154:155]
	s_mov_b32 m0, s42
	s_nop 0
	global_load_lds_dwordx4 v[184:185], off
	v_lshl_add_u64 v[184:185], s[40:41], 0, v[158:159]
	s_add_i32 m0, s42, 0x2000
	s_nop 0
	global_load_lds_dwordx4 v[184:185], off
	v_lshl_add_u64 v[184:185], v[220:221], 0, s[18:19]
	v_lshl_add_u64 v[184:185], v[222:223], 0, s[18:19]
	s_waitcnt vmcnt(8)
	s_waitcnt lgkmcnt(0)
	s_barrier
	s_setprio 1
	s_waitcnt lgkmcnt(0)
	v_mfma_f32_16x16x32_bf16 v[60:63], v[128:131], v[176:179], v[60:63]
	v_mfma_f32_16x16x32_bf16 v[56:59], v[136:139], v[176:179], v[56:59]
	v_mfma_f32_16x16x32_bf16 v[44:47], v[128:131], v[194:197], v[44:47]
	v_mfma_f32_16x16x32_bf16 v[40:43], v[136:139], v[194:197], v[40:43]
	v_mfma_f32_16x16x32_bf16 v[28:31], v[128:131], v[202:205], v[28:31]
	v_mfma_f32_16x16x32_bf16 v[24:27], v[136:139], v[202:205], v[24:27]
	v_mfma_f32_16x16x32_bf16 v[12:15], v[128:131], v[210:213], v[12:15]
	v_mfma_f32_16x16x32_bf16 v[8:11], v[136:139], v[210:213], v[8:11]
	v_mfma_f32_16x16x32_bf16 v[60:63], v[132:135], v[180:183], v[60:63]
	v_mfma_f32_16x16x32_bf16 v[56:59], v[140:143], v[180:183], v[56:59]
	v_mfma_f32_16x16x32_bf16 v[44:47], v[132:135], v[198:201], v[44:47]
	v_mfma_f32_16x16x32_bf16 v[40:43], v[140:143], v[198:201], v[40:43]
	v_mfma_f32_16x16x32_bf16 v[28:31], v[132:135], v[206:209], v[28:31]
	v_mfma_f32_16x16x32_bf16 v[24:27], v[140:143], v[206:209], v[24:27]
	v_mfma_f32_16x16x32_bf16 v[12:15], v[132:135], v[214:217], v[12:15]
	v_mfma_f32_16x16x32_bf16 v[8:11], v[140:143], v[214:217], v[8:11]
	s_setprio 0
	s_setprio 1
	v_mfma_f32_16x16x32_bf16 v[52:55], v[144:147], v[176:179], v[52:55]
	v_mfma_f32_16x16x32_bf16 v[48:51], v[168:171], v[176:179], v[48:51]
	v_mfma_f32_16x16x32_bf16 v[36:39], v[144:147], v[194:197], v[36:39]
	v_mfma_f32_16x16x32_bf16 v[32:35], v[168:171], v[194:197], v[32:35]
	v_mfma_f32_16x16x32_bf16 v[20:23], v[144:147], v[202:205], v[20:23]
	v_mfma_f32_16x16x32_bf16 v[16:19], v[168:171], v[202:205], v[16:19]
	v_mfma_f32_16x16x32_bf16 v[4:7], v[144:147], v[210:213], v[4:7]
	v_mfma_f32_16x16x32_bf16 v[0:3], v[168:171], v[210:213], v[0:3]
	v_mfma_f32_16x16x32_bf16 v[52:55], v[148:151], v[180:183], v[52:55]
	v_mfma_f32_16x16x32_bf16 v[48:51], v[172:175], v[180:183], v[48:51]
	v_mfma_f32_16x16x32_bf16 v[36:39], v[148:151], v[198:201], v[36:39]
	v_mfma_f32_16x16x32_bf16 v[32:35], v[172:175], v[198:201], v[32:35]
	v_mfma_f32_16x16x32_bf16 v[20:23], v[148:151], v[206:209], v[20:23]
	v_mfma_f32_16x16x32_bf16 v[16:19], v[172:175], v[206:209], v[16:19]
	v_mfma_f32_16x16x32_bf16 v[4:7], v[148:151], v[214:217], v[4:7]
	v_mfma_f32_16x16x32_bf16 v[0:3], v[172:175], v[214:217], v[0:3]
	s_setprio 0
	s_barrier
	s_add_i32 s57, s57, 2
	s_add_u32 s38, s38, 0x100
	s_addc_u32 s39, s39, 0
	s_add_u32 s55, s55, 0x100
	s_addc_u32 s56, s56, 0
	s_cmp_gt_u32 s57, 13
	s_cbranch_scc0 .LBB5_969
	s_nop 0
	s_nop 0
	s_nop 0
	s_nop 0
	s_nop 0
	s_nop 0
	s_nop 0
	s_nop 0
	s_nop 0
	s_nop 0
	s_nop 0
	s_nop 0
	s_nop 0
	s_nop 0
	s_nop 0
	s_nop 0
	s_nop 0
	s_nop 0
	s_nop 0
	s_nop 0
	s_nop 0
	s_nop 0
	s_and_b64 vcc, exec, s[16:17]
	s_cbranch_vccz .LBB5_972
	s_barrier
